# v25: P4/P8 residual+norm epilogues: 32 residual-tile loads through a 16-deep prefetch ring (loads-only counted waits), on top of v23
# speedup vs baseline: 1.0096x; 1.0096x over previous
; __device__ __forceinline__ unsigned pk2(float lo, float hi) { return cvt_pk_bf16(lo, hi); }
;     __device__ __forceinline__ void operator()(const f32x4 (&acc)[2][2][4][2], const Unit& u, int wr, int wc, int fr, int fq) const {
;         const int row0 = u.pm * 256 + wr * 64 + fr, col0 = u.pn * 256 + wc * 32 + 4 * fq;
;         f32x4 gv[2][2];
; #pragma unroll
;         for (int bj = 0; bj < 2; ++bj)
; #pragma unroll
;             for (int n = 0; n < 2; ++n) gv[bj][n] = *(const f32x4*)(gain + col0 + bj * 128 + n * 16);
; #pragma unroll
;         for (int ai = 0; ai < 2; ++ai)
; #pragma unroll
;             for (int m = 0; m < 4; ++m) {
;                 const int row = row0 + ai * 128 + m * 16; const size_t off = (size_t)row * D + col0;
;                 float s = 0.f;
; #pragma unroll
;                 for (int bj = 0; bj < 2; ++bj)
; #pragma unroll
;                     for (int n = 0; n < 2; ++n) { const f32x4 b = *(const f32x4*)(base + off + bj * 128 + n * 16); const f32x4 o = b + acc[ai][bj][m][n];
;                         *(f32x4*)(out + off + bj * 128 + n * 16) = o; s += (o[0] * o[0] + o[1] * o[1]) + (o[2] * o[2] + o[3] * o[3]);
;                         const f32x4 y = o * gv[bj][n]; u32x2 w; w.x = pk2(y[0], y[1]); w.y = pk2(y[2], y[3]); *(u32x2*)(xg + off + bj * 128 + n * 16) = w; }
;                 s += __shfl_xor(s, 16); s += __shfl_xor(s, 32);
;                 if (fq == 0) atomicAdd(ssq + row, s);
;             }
.LBB0_646:
	v_lshl_add_u32 v162, s66, 8, v1
	v_lshl_or_b32 v160, s68, 8, v165
	v_ashrrev_i32_e32 v163, 31, v162
	v_ashrrev_i32_e32 v161, 31, v160
	v_lshlrev_b64 v[74:75], 11, v[162:163]
	v_lshl_add_u64 v[158:159], v[74:75], 0, v[160:161]
	v_lshlrev_b64 v[174:175], 2, v[158:159]
	v_lshl_add_u64 v[176:177], s[42:43], 0, v[174:175]
	v_lshl_add_u64 v[74:75], v[160:161], 2, s[44:45]
	flat_load_dwordx4 v[94:97], v[74:75]
	flat_load_dwordx4 v[90:93], v[74:75] offset:64
	flat_load_dwordx4 v[82:85], v[74:75] offset:512
	s_nop 0
	flat_load_dwordx4 v[74:77], v[74:75] offset:576
	v_lshlrev_b32_e32 v250, 2, v158
	global_load_dwordx4 v[184:187], v250, s[42:43]
	global_load_dwordx4 v[188:191], v250, s[42:43] offset:64
	global_load_dwordx4 v[192:195], v250, s[42:43] offset:512
	global_load_dwordx4 v[196:199], v250, s[42:43] offset:576
	v_add_u32_e32 v251, 0x20000, v250
	global_load_dwordx4 v[200:203], v251, s[42:43]
	v_add_u32_e32 v251, 0x20000, v250
	global_load_dwordx4 v[204:207], v251, s[42:43] offset:64
	v_add_u32_e32 v251, 0x20000, v250
	global_load_dwordx4 v[208:211], v251, s[42:43] offset:512
	v_add_u32_e32 v251, 0x20000, v250
	global_load_dwordx4 v[212:215], v251, s[42:43] offset:576
	v_add_u32_e32 v251, 0x40000, v250
	global_load_dwordx4 v[216:219], v251, s[42:43]
	v_add_u32_e32 v251, 0x40000, v250
	global_load_dwordx4 v[220:223], v251, s[42:43] offset:64
	v_add_u32_e32 v251, 0x40000, v250
	global_load_dwordx4 v[224:227], v251, s[42:43] offset:512
	v_add_u32_e32 v251, 0x40000, v250
	global_load_dwordx4 v[228:231], v251, s[42:43] offset:576
	v_add_u32_e32 v251, 0x60000, v250
	global_load_dwordx4 v[232:235], v251, s[42:43]
	v_add_u32_e32 v251, 0x60000, v250
	global_load_dwordx4 v[236:239], v251, s[42:43] offset:64
	v_add_u32_e32 v251, 0x60000, v250
	global_load_dwordx4 v[240:243], v251, s[42:43] offset:512
	v_add_u32_e32 v251, 0x60000, v250
	global_load_dwordx4 v[244:247], v251, s[42:43] offset:576
	v_lshl_add_u64 v[178:179], v[158:159], 1, s[48:49]
	v_lshl_add_u64 v[180:181], s[12:13], 0, v[174:175]
	s_waitcnt vmcnt(15) lgkmcnt(0)
	s_nop 1
	v_mov_b64_e32 v[170:171], v[184:185]
	v_mov_b64_e32 v[172:173], v[186:187]
	v_add_u32_e32 v251, 0x100000, v250
	global_load_dwordx4 v[184:187], v251, s[42:43]
	v_pk_add_f32 v[142:143], v[142:143], v[170:171]
	v_pk_add_f32 v[144:145], v[144:145], v[172:173]
	v_pk_mul_f32 v[172:173], v[94:95], v[142:143]
	global_store_dwordx4 v[180:181], v[142:145], off
	v_pk_mul_f32 v[170:171], v[96:97], v[144:145]
	v_cvt_pk_bf16_f32 v172, v172, v173
	s_nop 0
	v_cvt_pk_bf16_f32 v173, v170, v171
	global_store_dwordx2 v[178:179], v[172:173], off
	s_waitcnt vmcnt(15) lgkmcnt(0)
	s_nop 1
	v_mov_b64_e32 v[170:171], v[188:189]
	v_mov_b64_e32 v[172:173], v[190:191]
	v_add_u32_e32 v251, 0x100000, v250
	global_load_dwordx4 v[188:191], v251, s[42:43] offset:64
	v_pk_add_f32 v[138:139], v[138:139], v[170:171]
	v_pk_add_f32 v[140:141], v[140:141], v[172:173]
	v_pk_mul_f32 v[172:173], v[90:91], v[138:139]
	global_store_dwordx4 v[180:181], v[138:141], off offset:64
	v_pk_mul_f32 v[170:171], v[92:93], v[140:141]
	v_cvt_pk_bf16_f32 v172, v172, v173
	s_nop 0
	v_cvt_pk_bf16_f32 v173, v170, v171
	global_store_dwordx2 v[178:179], v[172:173], off offset:32
	v_mul_f32_e32 v139, v139, v139
	v_mul_f32_e32 v141, v141, v141
	v_fmac_f32_e32 v139, v138, v138
	v_fmac_f32_e32 v141, v140, v140
	v_add_f32_e32 v138, v139, v141
	s_waitcnt vmcnt(15) lgkmcnt(0)
	s_nop 1
	v_mov_b64_e32 v[170:171], v[192:193]
	v_mov_b64_e32 v[172:173], v[194:195]
	v_add_u32_e32 v251, 0x100000, v250
	global_load_dwordx4 v[192:195], v251, s[42:43] offset:512
	v_pk_add_f32 v[170:171], v[134:135], v[170:171]
	v_pk_add_f32 v[172:173], v[136:137], v[172:173]
	v_pk_mul_f32 v[136:137], v[82:83], v[170:171]
	global_store_dwordx4 v[180:181], v[170:173], off offset:512
	v_pk_mul_f32 v[134:135], v[84:85], v[172:173]
	v_cvt_pk_bf16_f32 v136, v136, v137
	v_mul_f32_e32 v139, v173, v173
	v_cvt_pk_bf16_f32 v137, v134, v135
	global_store_dwordx2 v[178:179], v[136:137], off offset:256
	v_mul_f32_e32 v137, v143, v143
	v_mul_f32_e32 v143, v145, v145
	v_fmac_f32_e32 v137, v142, v142
	v_fmac_f32_e32 v143, v144, v144
	v_add_f32_e32 v137, v137, v143
	v_add_f32_e32 v137, v137, v138
	v_mul_f32_e32 v138, v171, v171
	v_fmac_f32_e32 v138, v170, v170
	v_fmac_f32_e32 v139, v172, v172
	v_and_b32_e32 v135, 64, v169
	v_add_f32_e32 v138, v138, v139
	v_xor_b32_e32 v134, 16, v169
	v_add_u32_e32 v135, 64, v135
	v_add_f32_e32 v137, v137, v138
	v_cmp_lt_i32_e32 vcc, v134, v135
	v_xor_b32_e32 v136, 32, v169
	s_waitcnt vmcnt(15) lgkmcnt(0)
	s_nop 1
	v_mov_b64_e32 v[174:175], v[196:197]
	v_mov_b64_e32 v[176:177], v[198:199]
	v_add_u32_e32 v251, 0x100000, v250
	global_load_dwordx4 v[196:199], v251, s[42:43] offset:576
	v_pk_add_f32 v[132:133], v[132:133], v[176:177]
	v_pk_add_f32 v[130:131], v[130:131], v[174:175]
	v_mul_f32_e32 v139, v133, v133
	v_mul_f32_e32 v138, v131, v131
	v_fmac_f32_e32 v138, v130, v130
	v_fmac_f32_e32 v139, v132, v132
	v_cndmask_b32_e32 v134, v169, v134, vcc
	v_add_f32_e32 v138, v138, v139
	v_lshlrev_b32_e32 v134, 2, v134
	v_add_f32_e32 v138, v137, v138
	ds_bpermute_b32 v139, v134, v138
	v_cmp_lt_i32_e32 vcc, v136, v135
	global_store_dwordx4 v[180:181], v[130:133], off offset:576
	s_nop 0
	v_cndmask_b32_e32 v135, v169, v136, vcc
	v_pk_mul_f32 v[136:137], v[76:77], v[132:133]
	s_waitcnt lgkmcnt(0)
	v_add_f32_e32 v133, v138, v139
	v_lshlrev_b32_e32 v132, 2, v135
	ds_bpermute_b32 v135, v132, v133
	v_pk_mul_f32 v[130:131], v[74:75], v[130:131]
	s_nop 0
	v_cvt_pk_bf16_f32 v130, v130, v131
	v_cvt_pk_bf16_f32 v131, v136, v137
	global_store_dwordx2 v[178:179], v[130:131], off offset:288
	v_lshl_add_u64 v[130:131], v[162:163], 2, s[14:15]
	s_and_saveexec_b64 s[66:67], s[2:3]
	s_cbranch_execz .LBB0_648
	s_waitcnt lgkmcnt(0)
	v_add_f32_e32 v133, v133, v135
	global_atomic_add_f32 v[130:131], v133, off
; __device__ __forceinline__ unsigned pk2(float lo, float hi) { return cvt_pk_bf16(lo, hi); }
;     __device__ __forceinline__ void operator()(const f32x4 (&acc)[2][2][4][2], const Unit& u, int wr, int wc, int fr, int fq) const {
;     ...
;         for (int ai = 0; ai < 2; ++ai)
; #pragma unroll
;             for (int m = 0; m < 4; ++m) {
;                 const int row = row0 + ai * 128 + m * 16; const size_t off = (size_t)row * D + col0;
;                 float s = 0.f;
; #pragma unroll
;                 for (int bj = 0; bj < 2; ++bj)
; #pragma unroll
;                     for (int n = 0; n < 2; ++n) { const f32x4 b = *(const f32x4*)(base + off + bj * 128 + n * 16); const f32x4 o = b + acc[ai][bj][m][n];
;                         *(f32x4*)(out + off + bj * 128 + n * 16) = o; s += (o[0] * o[0] + o[1] * o[1]) + (o[2] * o[2] + o[3] * o[3]);
;                         const f32x4 y = o * gv[bj][n]; u32x2 w; w.x = pk2(y[0], y[1]); w.y = pk2(y[2], y[3]); *(u32x2*)(xg + off + bj * 128 + n * 16) = w; }
;                 s += __shfl_xor(s, 16); s += __shfl_xor(s, 32);
;                 if (fq == 0) atomicAdd(ssq + row, s);
;             }
.LBB0_648:
	s_or_b64 exec, exec, s[66:67]
	v_or_b32_e32 v136, 16, v162
	v_ashrrev_i32_e32 v137, 31, v136
	v_lshlrev_b64 v[136:137], 11, v[136:137]
	v_lshl_add_u64 v[140:141], v[136:137], 0, v[160:161]
	v_lshlrev_b64 v[142:143], 2, v[140:141]
	v_lshl_add_u64 v[144:145], s[42:43], 0, v[142:143]
	v_lshl_add_u64 v[140:141], v[140:141], 1, s[48:49]
	v_lshl_add_u64 v[142:143], s[12:13], 0, v[142:143]
	s_waitcnt vmcnt(15) lgkmcnt(0)
	s_nop 1
	v_mov_b64_e32 v[136:137], v[200:201]
	v_mov_b64_e32 v[138:139], v[202:203]
	v_add_u32_e32 v251, 0x120000, v250
	global_load_dwordx4 v[200:203], v251, s[42:43]
	v_pk_add_f32 v[126:127], v[126:127], v[136:137]
	v_pk_add_f32 v[128:129], v[128:129], v[138:139]
	v_pk_mul_f32 v[138:139], v[94:95], v[126:127]
	global_store_dwordx4 v[142:143], v[126:129], off
	v_pk_mul_f32 v[136:137], v[96:97], v[128:129]
	v_cvt_pk_bf16_f32 v138, v138, v139
	s_nop 0
	v_cvt_pk_bf16_f32 v139, v136, v137
	global_store_dwordx2 v[140:141], v[138:139], off
	v_mul_f32_e32 v127, v127, v127
	v_mul_f32_e32 v129, v129, v129
	v_fmac_f32_e32 v127, v126, v126
	v_fmac_f32_e32 v129, v128, v128
	v_add_f32_e32 v126, v127, v129
	s_waitcnt vmcnt(15) lgkmcnt(0)
	s_nop 1
	v_mov_b64_e32 v[136:137], v[204:205]
	v_mov_b64_e32 v[138:139], v[206:207]
	v_add_u32_e32 v251, 0x120000, v250
	global_load_dwordx4 v[204:207], v251, s[42:43] offset:64
	v_pk_add_f32 v[122:123], v[122:123], v[136:137]
	v_pk_add_f32 v[124:125], v[124:125], v[138:139]
	v_pk_mul_f32 v[138:139], v[90:91], v[122:123]
	global_store_dwordx4 v[142:143], v[122:125], off offset:64
	v_pk_mul_f32 v[136:137], v[92:93], v[124:125]
	v_cvt_pk_bf16_f32 v138, v138, v139
	s_nop 0
	v_cvt_pk_bf16_f32 v139, v136, v137
	global_store_dwordx2 v[140:141], v[138:139], off offset:32
	v_mul_f32_e32 v123, v123, v123
	v_mul_f32_e32 v125, v125, v125
	v_fmac_f32_e32 v123, v122, v122
	v_fmac_f32_e32 v125, v124, v124
	v_add_f32_e32 v122, v123, v125
	v_add_f32_e32 v122, v126, v122
	s_waitcnt vmcnt(15) lgkmcnt(0)
	s_nop 1
	v_mov_b64_e32 v[136:137], v[208:209]
	v_mov_b64_e32 v[138:139], v[210:211]
	v_add_u32_e32 v251, 0x120000, v250
	global_load_dwordx4 v[208:211], v251, s[42:43] offset:512
	v_pk_add_f32 v[118:119], v[118:119], v[136:137]
	v_pk_add_f32 v[120:121], v[120:121], v[138:139]
	v_pk_mul_f32 v[138:139], v[82:83], v[118:119]
	global_store_dwordx4 v[142:143], v[118:121], off offset:512
	v_pk_mul_f32 v[136:137], v[84:85], v[120:121]
	v_cvt_pk_bf16_f32 v138, v138, v139
	s_nop 0
	v_cvt_pk_bf16_f32 v139, v136, v137
	global_store_dwordx2 v[140:141], v[138:139], off offset:256
	v_mul_f32_e32 v119, v119, v119
	v_mul_f32_e32 v121, v121, v121
	v_fmac_f32_e32 v119, v118, v118
	v_fmac_f32_e32 v121, v120, v120
	v_add_f32_e32 v118, v119, v121
	v_add_f32_e32 v120, v122, v118
	s_waitcnt vmcnt(15) lgkmcnt(0)
	s_nop 1
	v_mov_b64_e32 v[136:137], v[212:213]
	v_mov_b64_e32 v[138:139], v[214:215]
	v_add_u32_e32 v251, 0x120000, v250
	global_load_dwordx4 v[212:215], v251, s[42:43] offset:576
	v_pk_add_f32 v[118:119], v[116:117], v[138:139]
	v_pk_add_f32 v[116:117], v[114:115], v[136:137]
	v_mul_f32_e32 v115, v119, v119
	v_mul_f32_e32 v114, v117, v117
	v_fmac_f32_e32 v114, v116, v116
	v_fmac_f32_e32 v115, v118, v118
	v_add_f32_e32 v114, v114, v115
	v_add_f32_e32 v114, v120, v114
	ds_bpermute_b32 v115, v134, v114
	global_store_dwordx4 v[142:143], v[116:119], off offset:576
	s_waitcnt lgkmcnt(0)
	v_add_f32_e32 v114, v114, v115
	ds_bpermute_b32 v115, v132, v114
	v_pk_mul_f32 v[116:117], v[74:75], v[116:117]
	v_pk_mul_f32 v[118:119], v[76:77], v[118:119]
	v_cvt_pk_bf16_f32 v116, v116, v117
	s_nop 0
	v_cvt_pk_bf16_f32 v117, v118, v119
	global_store_dwordx2 v[140:141], v[116:117], off offset:288
	s_and_saveexec_b64 s[66:67], s[2:3]
	s_cbranch_execz .LBB0_650
	s_waitcnt lgkmcnt(0)
	v_add_f32_e32 v114, v114, v115
	global_atomic_add_f32 v[130:131], v114, off offset:64
.LBB0_650:
	s_or_b64 exec, exec, s[66:67]
	v_or_b32_e32 v114, 32, v162
	s_waitcnt lgkmcnt(0)
	v_ashrrev_i32_e32 v115, 31, v114
	v_lshlrev_b64 v[114:115], 11, v[114:115]
	v_lshl_add_u64 v[118:119], v[114:115], 0, v[160:161]
	v_lshlrev_b64 v[120:121], 2, v[118:119]
	v_lshl_add_u64 v[122:123], s[42:43], 0, v[120:121]
	v_lshl_add_u64 v[118:119], v[118:119], 1, s[48:49]
	v_lshl_add_u64 v[120:121], s[12:13], 0, v[120:121]
	s_waitcnt vmcnt(15) lgkmcnt(0)
	s_nop 1
	v_mov_b64_e32 v[114:115], v[216:217]
	v_mov_b64_e32 v[116:117], v[218:219]
	v_add_u32_e32 v251, 0x140000, v250
	global_load_dwordx4 v[216:219], v251, s[42:43]
	v_pk_add_f32 v[110:111], v[110:111], v[114:115]
	v_pk_add_f32 v[112:113], v[112:113], v[116:117]
	v_pk_mul_f32 v[116:117], v[94:95], v[110:111]
	global_store_dwordx4 v[120:121], v[110:113], off
	v_pk_mul_f32 v[114:115], v[96:97], v[112:113]
	v_cvt_pk_bf16_f32 v116, v116, v117
	s_nop 0
	v_cvt_pk_bf16_f32 v117, v114, v115
	global_store_dwordx2 v[118:119], v[116:117], off
	v_mul_f32_e32 v111, v111, v111
	v_mul_f32_e32 v113, v113, v113
	v_fmac_f32_e32 v111, v110, v110
	v_fmac_f32_e32 v113, v112, v112
	v_add_f32_e32 v110, v111, v113
	s_waitcnt vmcnt(15) lgkmcnt(0)
	s_nop 1
	v_mov_b64_e32 v[114:115], v[220:221]
	v_mov_b64_e32 v[116:117], v[222:223]
	v_add_u32_e32 v251, 0x140000, v250
	global_load_dwordx4 v[220:223], v251, s[42:43] offset:64
	v_pk_add_f32 v[106:107], v[106:107], v[114:115]
	v_pk_add_f32 v[108:109], v[108:109], v[116:117]
	v_pk_mul_f32 v[116:117], v[90:91], v[106:107]
	global_store_dwordx4 v[120:121], v[106:109], off offset:64
	v_pk_mul_f32 v[114:115], v[92:93], v[108:109]
	v_cvt_pk_bf16_f32 v116, v116, v117
	s_nop 0
	v_cvt_pk_bf16_f32 v117, v114, v115
	global_store_dwordx2 v[118:119], v[116:117], off offset:32
	v_mul_f32_e32 v107, v107, v107
	v_mul_f32_e32 v109, v109, v109
	v_fmac_f32_e32 v107, v106, v106
	v_fmac_f32_e32 v109, v108, v108
	v_add_f32_e32 v106, v107, v109
	v_add_f32_e32 v106, v110, v106
	s_waitcnt vmcnt(15) lgkmcnt(0)
; __device__ __forceinline__ unsigned pk2(float lo, float hi) { return cvt_pk_bf16(lo, hi); }
;     __device__ __forceinline__ void operator()(const f32x4 (&acc)[2][2][4][2], const Unit& u, int wr, int wc, int fr, int fq) const {
;     ...
;         for (int ai = 0; ai < 2; ++ai)
; #pragma unroll
;             for (int m = 0; m < 4; ++m) {
;                 const int row = row0 + ai * 128 + m * 16; const size_t off = (size_t)row * D + col0;
;                 float s = 0.f;
; #pragma unroll
;                 for (int bj = 0; bj < 2; ++bj)
; #pragma unroll
;                     for (int n = 0; n < 2; ++n) { const f32x4 b = *(const f32x4*)(base + off + bj * 128 + n * 16); const f32x4 o = b + acc[ai][bj][m][n];
;                         *(f32x4*)(out + off + bj * 128 + n * 16) = o; s += (o[0] * o[0] + o[1] * o[1]) + (o[2] * o[2] + o[3] * o[3]);
;                         const f32x4 y = o * gv[bj][n]; u32x2 w; w.x = pk2(y[0], y[1]); w.y = pk2(y[2], y[3]); *(u32x2*)(xg + off + bj * 128 + n * 16) = w; }
;                 s += __shfl_xor(s, 16); s += __shfl_xor(s, 32);
;                 if (fq == 0) atomicAdd(ssq + row, s);
;             }
	s_nop 1
	v_mov_b64_e32 v[114:115], v[224:225]
	v_mov_b64_e32 v[116:117], v[226:227]
	v_add_u32_e32 v251, 0x140000, v250
	global_load_dwordx4 v[224:227], v251, s[42:43] offset:512
	v_pk_add_f32 v[102:103], v[102:103], v[114:115]
	v_pk_add_f32 v[104:105], v[104:105], v[116:117]
	v_pk_mul_f32 v[116:117], v[82:83], v[102:103]
	global_store_dwordx4 v[120:121], v[102:105], off offset:512
	v_pk_mul_f32 v[114:115], v[84:85], v[104:105]
	v_cvt_pk_bf16_f32 v116, v116, v117
	s_nop 0
	v_cvt_pk_bf16_f32 v117, v114, v115
	global_store_dwordx2 v[118:119], v[116:117], off offset:256
	v_mul_f32_e32 v103, v103, v103
	v_mul_f32_e32 v105, v105, v105
	v_fmac_f32_e32 v103, v102, v102
	v_fmac_f32_e32 v105, v104, v104
	v_add_f32_e32 v102, v103, v105
	v_add_f32_e32 v104, v106, v102
	s_waitcnt vmcnt(15) lgkmcnt(0)
	s_nop 1
	v_mov_b64_e32 v[114:115], v[228:229]
	v_mov_b64_e32 v[116:117], v[230:231]
	v_add_u32_e32 v251, 0x140000, v250
	global_load_dwordx4 v[228:231], v251, s[42:43] offset:576
	v_pk_add_f32 v[102:103], v[100:101], v[116:117]
	v_pk_add_f32 v[100:101], v[98:99], v[114:115]
	v_mul_f32_e32 v99, v103, v103
	v_mul_f32_e32 v98, v101, v101
	v_fmac_f32_e32 v98, v100, v100
	v_fmac_f32_e32 v99, v102, v102
	v_add_f32_e32 v98, v98, v99
	v_add_f32_e32 v98, v104, v98
	ds_bpermute_b32 v99, v134, v98
	global_store_dwordx4 v[120:121], v[100:103], off offset:576
	s_waitcnt lgkmcnt(0)
	v_add_f32_e32 v98, v98, v99
	ds_bpermute_b32 v99, v132, v98
	v_pk_mul_f32 v[100:101], v[74:75], v[100:101]
	v_pk_mul_f32 v[102:103], v[76:77], v[102:103]
	v_cvt_pk_bf16_f32 v100, v100, v101
	s_nop 0
	v_cvt_pk_bf16_f32 v101, v102, v103
	global_store_dwordx2 v[118:119], v[100:101], off offset:288
	s_and_saveexec_b64 s[66:67], s[2:3]
	s_cbranch_execz .LBB0_652
	s_waitcnt lgkmcnt(0)
	v_add_f32_e32 v98, v98, v99
	global_atomic_add_f32 v[130:131], v98, off offset:128
.LBB0_652:
	s_or_b64 exec, exec, s[66:67]
	v_or_b32_e32 v98, 48, v162
	s_waitcnt lgkmcnt(0)
	v_ashrrev_i32_e32 v99, 31, v98
	v_lshlrev_b64 v[98:99], 11, v[98:99]
	v_lshl_add_u64 v[102:103], v[98:99], 0, v[160:161]
	v_lshlrev_b64 v[104:105], 2, v[102:103]
	v_lshl_add_u64 v[106:107], s[42:43], 0, v[104:105]
	v_lshl_add_u64 v[102:103], v[102:103], 1, s[48:49]
	v_lshl_add_u64 v[104:105], s[12:13], 0, v[104:105]
	s_waitcnt vmcnt(15) lgkmcnt(0)
	s_nop 1
	v_mov_b64_e32 v[98:99], v[232:233]
	v_mov_b64_e32 v[100:101], v[234:235]
	v_add_u32_e32 v251, 0x160000, v250
	global_load_dwordx4 v[232:235], v251, s[42:43]
	v_pk_add_f32 v[86:87], v[86:87], v[98:99]
	v_pk_add_f32 v[88:89], v[88:89], v[100:101]
	v_pk_mul_f32 v[100:101], v[94:95], v[86:87]
	global_store_dwordx4 v[104:105], v[86:89], off
	v_pk_mul_f32 v[98:99], v[96:97], v[88:89]
	v_cvt_pk_bf16_f32 v100, v100, v101
	s_nop 0
	v_cvt_pk_bf16_f32 v101, v98, v99
	global_store_dwordx2 v[102:103], v[100:101], off
	v_mul_f32_e32 v87, v87, v87
	v_mul_f32_e32 v89, v89, v89
	v_fmac_f32_e32 v87, v86, v86
	v_fmac_f32_e32 v89, v88, v88
	v_add_f32_e32 v86, v87, v89
	s_waitcnt vmcnt(15) lgkmcnt(0)
	s_nop 1
	v_mov_b64_e32 v[98:99], v[236:237]
	v_mov_b64_e32 v[100:101], v[238:239]
	v_add_u32_e32 v251, 0x160000, v250
	global_load_dwordx4 v[236:239], v251, s[42:43] offset:64
	v_pk_add_f32 v[78:79], v[78:79], v[98:99]
	v_pk_add_f32 v[80:81], v[80:81], v[100:101]
	v_pk_mul_f32 v[100:101], v[90:91], v[78:79]
	global_store_dwordx4 v[104:105], v[78:81], off offset:64
	v_pk_mul_f32 v[98:99], v[92:93], v[80:81]
	v_cvt_pk_bf16_f32 v100, v100, v101
	s_nop 0
	v_cvt_pk_bf16_f32 v101, v98, v99
	global_store_dwordx2 v[102:103], v[100:101], off offset:32
	v_mul_f32_e32 v79, v79, v79
	v_mul_f32_e32 v81, v81, v81
	v_fmac_f32_e32 v79, v78, v78
	v_fmac_f32_e32 v81, v80, v80
	v_add_f32_e32 v78, v79, v81
	v_add_f32_e32 v78, v86, v78
	s_waitcnt vmcnt(15) lgkmcnt(0)
	s_nop 1
	v_mov_b64_e32 v[98:99], v[240:241]
	v_mov_b64_e32 v[100:101], v[242:243]
	v_add_u32_e32 v251, 0x160000, v250
	global_load_dwordx4 v[240:243], v251, s[42:43] offset:512
	v_pk_add_f32 v[70:71], v[70:71], v[98:99]
	v_pk_add_f32 v[72:73], v[72:73], v[100:101]
	v_pk_mul_f32 v[100:101], v[82:83], v[70:71]
	global_store_dwordx4 v[104:105], v[70:73], off offset:512
	v_pk_mul_f32 v[98:99], v[84:85], v[72:73]
	v_cvt_pk_bf16_f32 v100, v100, v101
	s_nop 0
	v_cvt_pk_bf16_f32 v101, v98, v99
	global_store_dwordx2 v[102:103], v[100:101], off offset:256
	v_mul_f32_e32 v71, v71, v71
	v_mul_f32_e32 v73, v73, v73
	v_fmac_f32_e32 v71, v70, v70
	v_fmac_f32_e32 v73, v72, v72
	v_add_f32_e32 v70, v71, v73
	v_add_f32_e32 v72, v78, v70
	s_waitcnt vmcnt(15) lgkmcnt(0)
	s_nop 1
	v_mov_b64_e32 v[98:99], v[244:245]
	v_mov_b64_e32 v[100:101], v[246:247]
	v_add_u32_e32 v251, 0x160000, v250
	global_load_dwordx4 v[244:247], v251, s[42:43] offset:576
	v_pk_add_f32 v[70:71], v[68:69], v[100:101]
	v_pk_add_f32 v[68:69], v[66:67], v[98:99]
	v_mul_f32_e32 v67, v71, v71
	v_mul_f32_e32 v66, v69, v69
	v_fmac_f32_e32 v66, v68, v68
	v_fmac_f32_e32 v67, v70, v70
	v_add_f32_e32 v66, v66, v67
	v_add_f32_e32 v66, v72, v66
	ds_bpermute_b32 v67, v134, v66
	global_store_dwordx4 v[104:105], v[68:71], off offset:576
	s_waitcnt lgkmcnt(0)
	v_add_f32_e32 v66, v66, v67
	ds_bpermute_b32 v67, v132, v66
	v_pk_mul_f32 v[68:69], v[74:75], v[68:69]
	v_pk_mul_f32 v[70:71], v[76:77], v[70:71]
	v_cvt_pk_bf16_f32 v68, v68, v69
	s_nop 0
	v_cvt_pk_bf16_f32 v69, v70, v71
	global_store_dwordx2 v[102:103], v[68:69], off offset:288
	s_and_saveexec_b64 s[66:67], s[2:3]
	s_cbranch_execz .LBB0_654
	s_waitcnt lgkmcnt(0)
	v_add_f32_e32 v66, v66, v67
	global_atomic_add_f32 v[130:131], v66, off offset:192
; __device__ __forceinline__ unsigned pk2(float lo, float hi) { return cvt_pk_bf16(lo, hi); }
;     __device__ __forceinline__ void operator()(const f32x4 (&acc)[2][2][4][2], const Unit& u, int wr, int wc, int fr, int fq) const {
;     ...
;         for (int ai = 0; ai < 2; ++ai)
; #pragma unroll
;             for (int m = 0; m < 4; ++m) {
;                 const int row = row0 + ai * 128 + m * 16; const size_t off = (size_t)row * D + col0;
;                 float s = 0.f;
; #pragma unroll
;                 for (int bj = 0; bj < 2; ++bj)
; #pragma unroll
;                     for (int n = 0; n < 2; ++n) { const f32x4 b = *(const f32x4*)(base + off + bj * 128 + n * 16); const f32x4 o = b + acc[ai][bj][m][n];
;                         *(f32x4*)(out + off + bj * 128 + n * 16) = o; s += (o[0] * o[0] + o[1] * o[1]) + (o[2] * o[2] + o[3] * o[3]);
;                         const f32x4 y = o * gv[bj][n]; u32x2 w; w.x = pk2(y[0], y[1]); w.y = pk2(y[2], y[3]); *(u32x2*)(xg + off + bj * 128 + n * 16) = w; }
;                 s += __shfl_xor(s, 16); s += __shfl_xor(s, 32);
;                 if (fq == 0) atomicAdd(ssq + row, s);
;             }
.LBB0_654:
	s_or_b64 exec, exec, s[66:67]
	s_mov_b64 s[34:35], 0x40000
	v_lshl_add_u64 v[70:71], v[158:159], 0, s[34:35]
	v_lshlrev_b64 v[72:73], 2, v[70:71]
	v_lshl_add_u64 v[78:79], s[42:43], 0, v[72:73]
	s_waitcnt lgkmcnt(0)
	v_lshl_add_u64 v[70:71], v[70:71], 1, s[48:49]
	v_lshl_add_u64 v[72:73], s[12:13], 0, v[72:73]
	s_waitcnt vmcnt(15) lgkmcnt(0)
	s_nop 1
	v_mov_b64_e32 v[66:67], v[184:185]
	v_mov_b64_e32 v[68:69], v[186:187]
	v_pk_add_f32 v[62:63], v[62:63], v[66:67]
	v_pk_add_f32 v[64:65], v[64:65], v[68:69]
	v_pk_mul_f32 v[68:69], v[94:95], v[62:63]
	global_store_dwordx4 v[72:73], v[62:65], off
	v_pk_mul_f32 v[66:67], v[96:97], v[64:65]
	v_cvt_pk_bf16_f32 v68, v68, v69
	s_nop 0
	v_cvt_pk_bf16_f32 v69, v66, v67
	global_store_dwordx2 v[70:71], v[68:69], off
	v_mul_f32_e32 v63, v63, v63
	v_mul_f32_e32 v65, v65, v65
	v_fmac_f32_e32 v63, v62, v62
	v_fmac_f32_e32 v65, v64, v64
	v_add_f32_e32 v62, v63, v65
	s_waitcnt vmcnt(14) lgkmcnt(0)
	s_nop 1
	v_mov_b64_e32 v[66:67], v[188:189]
	v_mov_b64_e32 v[68:69], v[190:191]
	v_pk_add_f32 v[58:59], v[58:59], v[66:67]
	v_pk_add_f32 v[60:61], v[60:61], v[68:69]
	v_pk_mul_f32 v[68:69], v[90:91], v[58:59]
	global_store_dwordx4 v[72:73], v[58:61], off offset:64
	v_pk_mul_f32 v[66:67], v[92:93], v[60:61]
	v_cvt_pk_bf16_f32 v68, v68, v69
	s_nop 0
	v_cvt_pk_bf16_f32 v69, v66, v67
	global_store_dwordx2 v[70:71], v[68:69], off offset:32
	v_mul_f32_e32 v59, v59, v59
	v_mul_f32_e32 v61, v61, v61
	v_fmac_f32_e32 v59, v58, v58
	v_fmac_f32_e32 v61, v60, v60
	v_add_f32_e32 v58, v59, v61
	v_add_f32_e32 v58, v62, v58
	s_waitcnt vmcnt(13) lgkmcnt(0)
	s_nop 1
	v_mov_b64_e32 v[66:67], v[192:193]
	v_mov_b64_e32 v[68:69], v[194:195]
	v_pk_add_f32 v[54:55], v[54:55], v[66:67]
	v_pk_add_f32 v[56:57], v[56:57], v[68:69]
	v_pk_mul_f32 v[68:69], v[82:83], v[54:55]
	global_store_dwordx4 v[72:73], v[54:57], off offset:512
	v_pk_mul_f32 v[66:67], v[84:85], v[56:57]
	v_cvt_pk_bf16_f32 v68, v68, v69
	s_nop 0
	v_cvt_pk_bf16_f32 v69, v66, v67
	global_store_dwordx2 v[70:71], v[68:69], off offset:256
	v_mul_f32_e32 v55, v55, v55
	v_mul_f32_e32 v57, v57, v57
	v_fmac_f32_e32 v55, v54, v54
	v_fmac_f32_e32 v57, v56, v56
	v_add_f32_e32 v54, v55, v57
	v_add_f32_e32 v56, v58, v54
	s_waitcnt vmcnt(12) lgkmcnt(0)
	s_nop 1
	v_mov_b64_e32 v[66:67], v[196:197]
	v_mov_b64_e32 v[68:69], v[198:199]
	v_pk_add_f32 v[54:55], v[52:53], v[68:69]
	v_pk_add_f32 v[52:53], v[50:51], v[66:67]
	v_mul_f32_e32 v51, v55, v55
	v_mul_f32_e32 v50, v53, v53
	v_fmac_f32_e32 v50, v52, v52
	v_fmac_f32_e32 v51, v54, v54
	v_add_f32_e32 v50, v50, v51
	v_add_f32_e32 v50, v56, v50
	ds_bpermute_b32 v51, v134, v50
	global_store_dwordx4 v[72:73], v[52:55], off offset:576
	s_waitcnt lgkmcnt(0)
	v_add_f32_e32 v50, v50, v51
	ds_bpermute_b32 v51, v132, v50
	v_pk_mul_f32 v[52:53], v[74:75], v[52:53]
	v_pk_mul_f32 v[54:55], v[76:77], v[54:55]
	v_cvt_pk_bf16_f32 v52, v52, v53
	s_nop 0
	v_cvt_pk_bf16_f32 v53, v54, v55
	global_store_dwordx2 v[70:71], v[52:53], off offset:288
	s_and_saveexec_b64 s[66:67], s[2:3]
	s_cbranch_execz .LBB0_656
	s_waitcnt lgkmcnt(0)
	v_add_f32_e32 v50, v50, v51
	global_atomic_add_f32 v[130:131], v50, off offset:512
.LBB0_656:
	s_or_b64 exec, exec, s[66:67]
	s_mov_b64 s[34:35], 0x48000
	v_lshl_add_u64 v[54:55], v[158:159], 0, s[34:35]
	v_lshlrev_b64 v[56:57], 2, v[54:55]
	v_lshl_add_u64 v[58:59], s[42:43], 0, v[56:57]
	s_waitcnt lgkmcnt(0)
	v_lshl_add_u64 v[54:55], v[54:55], 1, s[48:49]
	v_lshl_add_u64 v[56:57], s[12:13], 0, v[56:57]
	s_waitcnt vmcnt(11) lgkmcnt(0)
	s_nop 1
	v_mov_b64_e32 v[50:51], v[200:201]
	v_mov_b64_e32 v[52:53], v[202:203]
	v_pk_add_f32 v[46:47], v[46:47], v[50:51]
	v_pk_add_f32 v[48:49], v[48:49], v[52:53]
	v_pk_mul_f32 v[52:53], v[94:95], v[46:47]
	global_store_dwordx4 v[56:57], v[46:49], off
	v_pk_mul_f32 v[50:51], v[96:97], v[48:49]
	v_cvt_pk_bf16_f32 v52, v52, v53
	s_nop 0
	v_cvt_pk_bf16_f32 v53, v50, v51
	global_store_dwordx2 v[54:55], v[52:53], off
	v_mul_f32_e32 v47, v47, v47
	v_mul_f32_e32 v49, v49, v49
	v_fmac_f32_e32 v47, v46, v46
	v_fmac_f32_e32 v49, v48, v48
	v_add_f32_e32 v46, v47, v49
	s_waitcnt vmcnt(10) lgkmcnt(0)
	s_nop 1
	v_mov_b64_e32 v[50:51], v[204:205]
	v_mov_b64_e32 v[52:53], v[206:207]
	v_pk_add_f32 v[42:43], v[42:43], v[50:51]
	v_pk_add_f32 v[44:45], v[44:45], v[52:53]
	v_pk_mul_f32 v[52:53], v[90:91], v[42:43]
	global_store_dwordx4 v[56:57], v[42:45], off offset:64
	v_pk_mul_f32 v[50:51], v[92:93], v[44:45]
	v_cvt_pk_bf16_f32 v52, v52, v53
	s_nop 0
	v_cvt_pk_bf16_f32 v53, v50, v51
	global_store_dwordx2 v[54:55], v[52:53], off offset:32
	v_mul_f32_e32 v43, v43, v43
	v_mul_f32_e32 v45, v45, v45
	v_fmac_f32_e32 v43, v42, v42
	v_fmac_f32_e32 v45, v44, v44
	v_add_f32_e32 v42, v43, v45
	v_add_f32_e32 v42, v46, v42
	s_waitcnt vmcnt(9) lgkmcnt(0)
	s_nop 1
	v_mov_b64_e32 v[50:51], v[208:209]
	v_mov_b64_e32 v[52:53], v[210:211]
	v_pk_add_f32 v[38:39], v[38:39], v[50:51]
	v_pk_add_f32 v[40:41], v[40:41], v[52:53]
	v_pk_mul_f32 v[52:53], v[82:83], v[38:39]
	global_store_dwordx4 v[56:57], v[38:41], off offset:512
	v_pk_mul_f32 v[50:51], v[84:85], v[40:41]
	v_cvt_pk_bf16_f32 v52, v52, v53
	s_nop 0
	v_cvt_pk_bf16_f32 v53, v50, v51
	global_store_dwordx2 v[54:55], v[52:53], off offset:256
	v_mul_f32_e32 v39, v39, v39
	v_mul_f32_e32 v41, v41, v41
	v_fmac_f32_e32 v39, v38, v38
	v_fmac_f32_e32 v41, v40, v40
	v_add_f32_e32 v38, v39, v41
	v_add_f32_e32 v40, v42, v38
	s_waitcnt vmcnt(8) lgkmcnt(0)
	s_nop 1
	v_mov_b64_e32 v[50:51], v[212:213]
	v_mov_b64_e32 v[52:53], v[214:215]
	v_pk_add_f32 v[38:39], v[36:37], v[52:53]
	v_pk_add_f32 v[36:37], v[34:35], v[50:51]
	v_mul_f32_e32 v35, v39, v39
	v_mul_f32_e32 v34, v37, v37
	v_fmac_f32_e32 v34, v36, v36
	v_fmac_f32_e32 v35, v38, v38
	v_add_f32_e32 v34, v34, v35
	v_add_f32_e32 v34, v40, v34
	ds_bpermute_b32 v35, v134, v34
	global_store_dwordx4 v[56:57], v[36:39], off offset:576
	s_waitcnt lgkmcnt(0)
	v_add_f32_e32 v34, v34, v35
	ds_bpermute_b32 v35, v132, v34
	v_pk_mul_f32 v[36:37], v[74:75], v[36:37]
	v_pk_mul_f32 v[38:39], v[76:77], v[38:39]
	v_cvt_pk_bf16_f32 v36, v36, v37
	s_nop 0
	v_cvt_pk_bf16_f32 v37, v38, v39
	global_store_dwordx2 v[54:55], v[36:37], off offset:288
	s_and_saveexec_b64 s[66:67], s[2:3]
	s_cbranch_execz .LBB0_658
	s_waitcnt lgkmcnt(0)
	v_add_f32_e32 v34, v34, v35
	global_atomic_add_f32 v[130:131], v34, off offset:576
; __device__ __forceinline__ unsigned pk2(float lo, float hi) { return cvt_pk_bf16(lo, hi); }
;     __device__ __forceinline__ void operator()(const f32x4 (&acc)[2][2][4][2], const Unit& u, int wr, int wc, int fr, int fq) const {
;     ...
;         for (int ai = 0; ai < 2; ++ai)
; #pragma unroll
;             for (int m = 0; m < 4; ++m) {
;                 const int row = row0 + ai * 128 + m * 16; const size_t off = (size_t)row * D + col0;
;                 float s = 0.f;
; #pragma unroll
;                 for (int bj = 0; bj < 2; ++bj)
; #pragma unroll
;                     for (int n = 0; n < 2; ++n) { const f32x4 b = *(const f32x4*)(base + off + bj * 128 + n * 16); const f32x4 o = b + acc[ai][bj][m][n];
;                         *(f32x4*)(out + off + bj * 128 + n * 16) = o; s += (o[0] * o[0] + o[1] * o[1]) + (o[2] * o[2] + o[3] * o[3]);
;                         const f32x4 y = o * gv[bj][n]; u32x2 w; w.x = pk2(y[0], y[1]); w.y = pk2(y[2], y[3]); *(u32x2*)(xg + off + bj * 128 + n * 16) = w; }
;                 s += __shfl_xor(s, 16); s += __shfl_xor(s, 32);
;                 if (fq == 0) atomicAdd(ssq + row, s);
;             }
.LBB0_658:
	s_or_b64 exec, exec, s[66:67]
	s_mov_b64 s[34:35], 0x50000
	v_lshl_add_u64 v[38:39], v[158:159], 0, s[34:35]
	v_lshlrev_b64 v[40:41], 2, v[38:39]
	v_lshl_add_u64 v[42:43], s[42:43], 0, v[40:41]
	s_waitcnt lgkmcnt(0)
	v_lshl_add_u64 v[38:39], v[38:39], 1, s[48:49]
	v_lshl_add_u64 v[40:41], s[12:13], 0, v[40:41]
	s_waitcnt vmcnt(7) lgkmcnt(0)
	s_nop 1
	v_mov_b64_e32 v[34:35], v[216:217]
	v_mov_b64_e32 v[36:37], v[218:219]
	v_pk_add_f32 v[30:31], v[30:31], v[34:35]
	v_pk_add_f32 v[32:33], v[32:33], v[36:37]
	v_pk_mul_f32 v[36:37], v[94:95], v[30:31]
	global_store_dwordx4 v[40:41], v[30:33], off
	v_pk_mul_f32 v[34:35], v[96:97], v[32:33]
	v_cvt_pk_bf16_f32 v36, v36, v37
	s_nop 0
	v_cvt_pk_bf16_f32 v37, v34, v35
	global_store_dwordx2 v[38:39], v[36:37], off
	v_mul_f32_e32 v31, v31, v31
	v_mul_f32_e32 v33, v33, v33
	v_fmac_f32_e32 v31, v30, v30
	v_fmac_f32_e32 v33, v32, v32
	v_add_f32_e32 v30, v31, v33
	s_waitcnt vmcnt(6) lgkmcnt(0)
	s_nop 1
	v_mov_b64_e32 v[34:35], v[220:221]
	v_mov_b64_e32 v[36:37], v[222:223]
	v_pk_add_f32 v[26:27], v[26:27], v[34:35]
	v_pk_add_f32 v[28:29], v[28:29], v[36:37]
	v_pk_mul_f32 v[36:37], v[90:91], v[26:27]
	global_store_dwordx4 v[40:41], v[26:29], off offset:64
	v_pk_mul_f32 v[34:35], v[92:93], v[28:29]
	v_cvt_pk_bf16_f32 v36, v36, v37
	s_nop 0
	v_cvt_pk_bf16_f32 v37, v34, v35
	global_store_dwordx2 v[38:39], v[36:37], off offset:32
	v_mul_f32_e32 v27, v27, v27
	v_mul_f32_e32 v29, v29, v29
	v_fmac_f32_e32 v27, v26, v26
	v_fmac_f32_e32 v29, v28, v28
	v_add_f32_e32 v26, v27, v29
	v_add_f32_e32 v26, v30, v26
	s_waitcnt vmcnt(5) lgkmcnt(0)
	s_nop 1
	v_mov_b64_e32 v[34:35], v[224:225]
	v_mov_b64_e32 v[36:37], v[226:227]
	v_pk_add_f32 v[22:23], v[22:23], v[34:35]
	v_pk_add_f32 v[24:25], v[24:25], v[36:37]
	v_pk_mul_f32 v[36:37], v[82:83], v[22:23]
	global_store_dwordx4 v[40:41], v[22:25], off offset:512
	v_pk_mul_f32 v[34:35], v[84:85], v[24:25]
	v_cvt_pk_bf16_f32 v36, v36, v37
	s_nop 0
	v_cvt_pk_bf16_f32 v37, v34, v35
	global_store_dwordx2 v[38:39], v[36:37], off offset:256
	v_mul_f32_e32 v23, v23, v23
	v_mul_f32_e32 v25, v25, v25
	v_fmac_f32_e32 v23, v22, v22
	v_fmac_f32_e32 v25, v24, v24
	v_add_f32_e32 v22, v23, v25
	v_add_f32_e32 v24, v26, v22
	s_waitcnt vmcnt(4) lgkmcnt(0)
	s_nop 1
	v_mov_b64_e32 v[34:35], v[228:229]
	v_mov_b64_e32 v[36:37], v[230:231]
	v_pk_add_f32 v[22:23], v[20:21], v[36:37]
	v_pk_add_f32 v[20:21], v[18:19], v[34:35]
	v_mul_f32_e32 v19, v23, v23
	v_mul_f32_e32 v18, v21, v21
	v_fmac_f32_e32 v18, v20, v20
	v_fmac_f32_e32 v19, v22, v22
	v_add_f32_e32 v18, v18, v19
	v_add_f32_e32 v18, v24, v18
	ds_bpermute_b32 v19, v134, v18
	global_store_dwordx4 v[40:41], v[20:23], off offset:576
	s_waitcnt lgkmcnt(0)
	v_add_f32_e32 v18, v18, v19
	ds_bpermute_b32 v19, v132, v18
	v_pk_mul_f32 v[20:21], v[74:75], v[20:21]
	v_pk_mul_f32 v[22:23], v[76:77], v[22:23]
	v_cvt_pk_bf16_f32 v20, v20, v21
	s_nop 0
	v_cvt_pk_bf16_f32 v21, v22, v23
	global_store_dwordx2 v[38:39], v[20:21], off offset:288
	s_and_saveexec_b64 s[66:67], s[2:3]
	s_cbranch_execz .LBB0_660
	s_waitcnt lgkmcnt(0)
	v_add_f32_e32 v18, v18, v19
	global_atomic_add_f32 v[130:131], v18, off offset:640
.LBB0_660:
	s_or_b64 exec, exec, s[66:67]
	s_mov_b64 s[34:35], 0x58000
	v_lshl_add_u64 v[22:23], v[158:159], 0, s[34:35]
	v_lshlrev_b64 v[24:25], 2, v[22:23]
	v_lshl_add_u64 v[26:27], s[42:43], 0, v[24:25]
	s_waitcnt lgkmcnt(0)
	v_lshl_add_u64 v[22:23], v[22:23], 1, s[48:49]
	v_lshl_add_u64 v[24:25], s[12:13], 0, v[24:25]
	s_waitcnt vmcnt(3) lgkmcnt(0)
	s_nop 1
	v_mov_b64_e32 v[18:19], v[232:233]
	v_mov_b64_e32 v[20:21], v[234:235]
	v_pk_add_f32 v[14:15], v[14:15], v[18:19]
	v_pk_add_f32 v[16:17], v[16:17], v[20:21]
	v_pk_mul_f32 v[20:21], v[94:95], v[14:15]
	global_store_dwordx4 v[24:25], v[14:17], off
	v_pk_mul_f32 v[18:19], v[96:97], v[16:17]
	v_cvt_pk_bf16_f32 v20, v20, v21
	s_nop 0
	v_cvt_pk_bf16_f32 v21, v18, v19
	global_store_dwordx2 v[22:23], v[20:21], off
	v_mul_f32_e32 v15, v15, v15
	v_mul_f32_e32 v17, v17, v17
	v_fmac_f32_e32 v15, v14, v14
	v_fmac_f32_e32 v17, v16, v16
	v_add_f32_e32 v14, v15, v17
	s_waitcnt vmcnt(2) lgkmcnt(0)
	s_nop 1
	v_mov_b64_e32 v[18:19], v[236:237]
	v_mov_b64_e32 v[20:21], v[238:239]
	v_pk_add_f32 v[10:11], v[10:11], v[18:19]
	v_pk_add_f32 v[12:13], v[12:13], v[20:21]
	v_pk_mul_f32 v[20:21], v[90:91], v[10:11]
	global_store_dwordx4 v[24:25], v[10:13], off offset:64
	v_pk_mul_f32 v[18:19], v[92:93], v[12:13]
	v_cvt_pk_bf16_f32 v20, v20, v21
	s_nop 0
	v_cvt_pk_bf16_f32 v21, v18, v19
	global_store_dwordx2 v[22:23], v[20:21], off offset:32
	v_mul_f32_e32 v11, v11, v11
	v_mul_f32_e32 v13, v13, v13
	v_fmac_f32_e32 v11, v10, v10
	v_fmac_f32_e32 v13, v12, v12
	v_add_f32_e32 v10, v11, v13
	v_add_f32_e32 v10, v14, v10
	s_waitcnt vmcnt(1) lgkmcnt(0)
	s_nop 1
	v_mov_b64_e32 v[18:19], v[240:241]
	v_mov_b64_e32 v[20:21], v[242:243]
	v_pk_add_f32 v[6:7], v[6:7], v[18:19]
	v_pk_add_f32 v[8:9], v[8:9], v[20:21]
	v_pk_mul_f32 v[20:21], v[82:83], v[6:7]
	global_store_dwordx4 v[24:25], v[6:9], off offset:512
	v_pk_mul_f32 v[18:19], v[84:85], v[8:9]
	v_cvt_pk_bf16_f32 v20, v20, v21
	s_nop 0
	v_cvt_pk_bf16_f32 v21, v18, v19
	global_store_dwordx2 v[22:23], v[20:21], off offset:256
	v_mul_f32_e32 v7, v7, v7
	v_mul_f32_e32 v9, v9, v9
	v_fmac_f32_e32 v7, v6, v6
	v_fmac_f32_e32 v9, v8, v8
	v_add_f32_e32 v6, v7, v9
	v_add_f32_e32 v8, v10, v6
	s_waitcnt vmcnt(0) lgkmcnt(0)
	s_nop 1
	v_mov_b64_e32 v[18:19], v[244:245]
	v_mov_b64_e32 v[20:21], v[246:247]
	v_pk_add_f32 v[6:7], v[4:5], v[20:21]
	v_pk_add_f32 v[4:5], v[2:3], v[18:19]
	v_mul_f32_e32 v3, v7, v7
	v_mul_f32_e32 v2, v5, v5
	v_fmac_f32_e32 v2, v4, v4
	v_fmac_f32_e32 v3, v6, v6
	v_add_f32_e32 v2, v2, v3
	v_add_f32_e32 v2, v8, v2
	ds_bpermute_b32 v3, v134, v2
	global_store_dwordx4 v[24:25], v[4:7], off offset:576
	s_waitcnt lgkmcnt(0)
	v_add_f32_e32 v2, v2, v3
	ds_bpermute_b32 v3, v132, v2
	v_pk_mul_f32 v[4:5], v[74:75], v[4:5]
	v_pk_mul_f32 v[6:7], v[76:77], v[6:7]
	v_cvt_pk_bf16_f32 v4, v4, v5
	s_nop 0
	v_cvt_pk_bf16_f32 v5, v6, v7
	global_store_dwordx2 v[22:23], v[4:5], off offset:288
	s_and_saveexec_b64 s[66:67], s[2:3]
	s_cbranch_execz .LBB0_662
	s_waitcnt lgkmcnt(0)
	v_add_f32_e32 v2, v2, v3
	global_atomic_add_f32 v[130:131], v2, off offset:704

; __device__ __forceinline__ unsigned pk2(float lo, float hi) { return cvt_pk_bf16(lo, hi); }
;     __device__ __forceinline__ void operator()(const f32x4 (&acc)[2][2][4][2], const Unit& u, int wr, int wc, int fr, int fq) const {
;         const int row0 = u.pm * 256 + wr * 64 + fr, col0 = u.pn * 256 + wc * 32 + 4 * fq;
;         f32x4 gv[2][2];
; #pragma unroll
;         for (int bj = 0; bj < 2; ++bj)
; #pragma unroll
;             for (int n = 0; n < 2; ++n) gv[bj][n] = *(const f32x4*)(gain + col0 + bj * 128 + n * 16);
; #pragma unroll
;         for (int ai = 0; ai < 2; ++ai)
; #pragma unroll
;             for (int m = 0; m < 4; ++m) {
;                 const int row = row0 + ai * 128 + m * 16; const size_t off = (size_t)row * D + col0;
;                 float s = 0.f;
; #pragma unroll
;                 for (int bj = 0; bj < 2; ++bj)
; #pragma unroll
;                     for (int n = 0; n < 2; ++n) { const f32x4 b = *(const f32x4*)(base + off + bj * 128 + n * 16); const f32x4 o = b + acc[ai][bj][m][n];
;                         *(f32x4*)(out + off + bj * 128 + n * 16) = o; s += (o[0] * o[0] + o[1] * o[1]) + (o[2] * o[2] + o[3] * o[3]);
;                         const f32x4 y = o * gv[bj][n]; u32x2 w; w.x = pk2(y[0], y[1]); w.y = pk2(y[2], y[3]); *(u32x2*)(xg + off + bj * 128 + n * 16) = w; }
;                 s += __shfl_xor(s, 16); s += __shfl_xor(s, 32);
;                 if (fq == 0) atomicAdd(ssq + row, s);
;             }
.LBB0_923:
	v_lshl_add_u32 v160, s56, 8, v1
	v_lshl_or_b32 v158, s58, 8, v163
	v_ashrrev_i32_e32 v161, 31, v160
	v_ashrrev_i32_e32 v159, 31, v158
	v_lshlrev_b64 v[70:71], 11, v[160:161]
	v_lshl_add_u64 v[172:173], v[70:71], 0, v[158:159]
	v_lshl_add_u64 v[176:177], v[172:173], 2, s[12:13]
	v_lshl_add_u64 v[70:71], v[158:159], 2, s[34:35]
	flat_load_dwordx4 v[94:97], v[70:71]
	flat_load_dwordx4 v[90:93], v[70:71] offset:64
	flat_load_dwordx4 v[82:85], v[70:71] offset:512
	s_nop 0
	flat_load_dwordx4 v[70:73], v[70:71] offset:576
	v_lshlrev_b32_e32 v250, 2, v172
	global_load_dwordx4 v[184:187], v250, s[12:13]
	global_load_dwordx4 v[188:191], v250, s[12:13] offset:64
	global_load_dwordx4 v[192:195], v250, s[12:13] offset:512
	global_load_dwordx4 v[196:199], v250, s[12:13] offset:576
	v_add_u32_e32 v251, 0x20000, v250
	global_load_dwordx4 v[200:203], v251, s[12:13]
	v_add_u32_e32 v251, 0x20000, v250
	global_load_dwordx4 v[204:207], v251, s[12:13] offset:64
	v_add_u32_e32 v251, 0x20000, v250
	global_load_dwordx4 v[208:211], v251, s[12:13] offset:512
	v_add_u32_e32 v251, 0x20000, v250
	global_load_dwordx4 v[212:215], v251, s[12:13] offset:576
	v_add_u32_e32 v251, 0x40000, v250
	global_load_dwordx4 v[216:219], v251, s[12:13]
	v_add_u32_e32 v251, 0x40000, v250
	global_load_dwordx4 v[220:223], v251, s[12:13] offset:64
	v_add_u32_e32 v251, 0x40000, v250
	global_load_dwordx4 v[224:227], v251, s[12:13] offset:512
	v_add_u32_e32 v251, 0x40000, v250
	global_load_dwordx4 v[228:231], v251, s[12:13] offset:576
	v_add_u32_e32 v251, 0x60000, v250
	global_load_dwordx4 v[232:235], v251, s[12:13]
	v_add_u32_e32 v251, 0x60000, v250
	global_load_dwordx4 v[236:239], v251, s[12:13] offset:64
	v_add_u32_e32 v251, 0x60000, v250
	global_load_dwordx4 v[240:243], v251, s[12:13] offset:512
	v_add_u32_e32 v251, 0x60000, v250
	global_load_dwordx4 v[244:247], v251, s[12:13] offset:576
	v_lshl_add_u64 v[178:179], v[172:173], 1, s[30:31]
	v_xor_b32_e32 v180, 32, v167
	s_waitcnt vmcnt(15)
	s_nop 1
	v_mov_b64_e32 v[168:169], v[184:185]
	v_mov_b64_e32 v[170:171], v[186:187]
	v_add_u32_e32 v251, 0x100000, v250
	global_load_dwordx4 v[184:187], v251, s[12:13]
	v_pk_add_f32 v[142:143], v[142:143], v[168:169]
	v_pk_add_f32 v[144:145], v[144:145], v[170:171]
	s_waitcnt lgkmcnt(0)
	v_pk_mul_f32 v[170:171], v[94:95], v[142:143]
	global_store_dwordx4 v[176:177], v[142:145], off
	v_pk_mul_f32 v[168:169], v[96:97], v[144:145]
	v_cvt_pk_bf16_f32 v170, v170, v171
	s_nop 0
	v_cvt_pk_bf16_f32 v171, v168, v169
	global_store_dwordx2 v[178:179], v[170:171], off
	s_waitcnt vmcnt(15)
	s_nop 1
	v_mov_b64_e32 v[168:169], v[188:189]
	v_mov_b64_e32 v[170:171], v[190:191]
	v_add_u32_e32 v251, 0x100000, v250
	global_load_dwordx4 v[188:191], v251, s[12:13] offset:64
	v_pk_add_f32 v[138:139], v[138:139], v[168:169]
	v_pk_add_f32 v[140:141], v[140:141], v[170:171]
	v_pk_mul_f32 v[170:171], v[90:91], v[138:139]
	global_store_dwordx4 v[176:177], v[138:141], off offset:64
	v_pk_mul_f32 v[168:169], v[92:93], v[140:141]
	v_cvt_pk_bf16_f32 v170, v170, v171
	s_nop 0
	v_cvt_pk_bf16_f32 v171, v168, v169
	global_store_dwordx2 v[178:179], v[170:171], off offset:32
	s_waitcnt vmcnt(15)
	s_nop 1
	v_mov_b64_e32 v[168:169], v[192:193]
	v_mov_b64_e32 v[170:171], v[194:195]
	v_add_u32_e32 v251, 0x100000, v250
	global_load_dwordx4 v[192:195], v251, s[12:13] offset:512
	v_pk_add_f32 v[168:169], v[134:135], v[168:169]
	v_pk_add_f32 v[170:171], v[136:137], v[170:171]
	v_pk_mul_f32 v[136:137], v[82:83], v[168:169]
	global_store_dwordx4 v[176:177], v[168:171], off offset:512
	v_pk_mul_f32 v[134:135], v[84:85], v[170:171]
	v_cvt_pk_bf16_f32 v136, v136, v137
	s_nop 0
	v_cvt_pk_bf16_f32 v137, v134, v135
	global_store_dwordx2 v[178:179], v[136:137], off offset:256
	v_mul_f32_e32 v136, v143, v143
	v_mul_f32_e32 v137, v145, v145
	v_fmac_f32_e32 v136, v142, v142
	v_fmac_f32_e32 v137, v144, v144
	v_add_f32_e32 v136, v136, v137
	v_mul_f32_e32 v137, v139, v139
	v_mul_f32_e32 v139, v141, v141
	v_fmac_f32_e32 v137, v138, v138
	v_fmac_f32_e32 v139, v140, v140
	v_add_f32_e32 v137, v137, v139
	v_add_f32_e32 v136, v136, v137
	v_mul_f32_e32 v137, v169, v169
	v_mul_f32_e32 v138, v171, v171
	v_fmac_f32_e32 v137, v168, v168
	v_fmac_f32_e32 v138, v170, v170
	v_add_f32_e32 v137, v137, v138
	v_and_b32_e32 v135, 64, v167
	v_add_f32_e32 v140, v136, v137
	v_xor_b32_e32 v134, 16, v167
	v_add_u32_e32 v135, 64, v135
	v_cmp_lt_i32_e32 vcc, v134, v135
	s_waitcnt vmcnt(15)
	s_nop 1
	v_mov_b64_e32 v[172:173], v[196:197]
	v_mov_b64_e32 v[174:175], v[198:199]
	v_add_u32_e32 v251, 0x100000, v250
	global_load_dwordx4 v[196:199], v251, s[12:13] offset:576
	v_pk_add_f32 v[138:139], v[132:133], v[174:175]
	v_pk_add_f32 v[136:137], v[130:131], v[172:173]
	v_mul_f32_e32 v131, v139, v139
	v_mul_f32_e32 v130, v137, v137
	v_fmac_f32_e32 v130, v136, v136
	v_fmac_f32_e32 v131, v138, v138
	v_cndmask_b32_e32 v134, v167, v134, vcc
	v_add_f32_e32 v130, v130, v131
	v_lshlrev_b32_e32 v134, 2, v134
	v_add_f32_e32 v130, v140, v130
	ds_bpermute_b32 v131, v134, v130
	v_cmp_lt_i32_e32 vcc, v180, v135
	global_store_dwordx4 v[176:177], v[136:139], off offset:576
	s_waitcnt lgkmcnt(0)
	v_add_f32_e32 v130, v130, v131
	v_cndmask_b32_e32 v132, v167, v180, vcc
	v_lshlrev_b32_e32 v132, 2, v132
	ds_bpermute_b32 v131, v132, v130
	v_pk_mul_f32 v[136:137], v[70:71], v[136:137]
	v_pk_mul_f32 v[138:139], v[72:73], v[138:139]
	v_cvt_pk_bf16_f32 v136, v136, v137
	s_nop 0
	v_cvt_pk_bf16_f32 v137, v138, v139
	global_store_dwordx2 v[178:179], v[136:137], off offset:288
	s_and_saveexec_b64 s[56:57], s[2:3]
	s_cbranch_execz .LBB0_925
	v_lshl_add_u64 v[136:137], v[160:161], 2, s[6:7]
	s_waitcnt lgkmcnt(0)
	v_add_f32_e32 v130, v130, v131
	global_atomic_add_f32 v[136:137], v130, off
; __device__ __forceinline__ unsigned pk2(float lo, float hi) { return cvt_pk_bf16(lo, hi); }
;     __device__ __forceinline__ void operator()(const f32x4 (&acc)[2][2][4][2], const Unit& u, int wr, int wc, int fr, int fq) const {
;     ...
;         for (int ai = 0; ai < 2; ++ai)
; #pragma unroll
;             for (int m = 0; m < 4; ++m) {
;                 const int row = row0 + ai * 128 + m * 16; const size_t off = (size_t)row * D + col0;
;                 float s = 0.f;
; #pragma unroll
;                 for (int bj = 0; bj < 2; ++bj)
; #pragma unroll
;                     for (int n = 0; n < 2; ++n) { const f32x4 b = *(const f32x4*)(base + off + bj * 128 + n * 16); const f32x4 o = b + acc[ai][bj][m][n];
;                         *(f32x4*)(out + off + bj * 128 + n * 16) = o; s += (o[0] * o[0] + o[1] * o[1]) + (o[2] * o[2] + o[3] * o[3]);
;                         const f32x4 y = o * gv[bj][n]; u32x2 w; w.x = pk2(y[0], y[1]); w.y = pk2(y[2], y[3]); *(u32x2*)(xg + off + bj * 128 + n * 16) = w; }
;                 s += __shfl_xor(s, 16); s += __shfl_xor(s, 32);
;                 if (fq == 0) atomicAdd(ssq + row, s);
;             }
.LBB0_925:
	s_or_b64 exec, exec, s[56:57]
	v_or_b32_e32 v130, 16, v160
	s_waitcnt lgkmcnt(0)
	v_ashrrev_i32_e32 v131, 31, v130
	v_lshlrev_b64 v[136:137], 11, v[130:131]
	v_lshl_add_u64 v[140:141], v[136:137], 0, v[158:159]
	v_lshl_add_u64 v[142:143], v[140:141], 2, s[12:13]
	v_lshl_add_u64 v[140:141], v[140:141], 1, s[30:31]
	s_waitcnt vmcnt(15)
	s_nop 1
	v_mov_b64_e32 v[136:137], v[200:201]
	v_mov_b64_e32 v[138:139], v[202:203]
	v_add_u32_e32 v251, 0x120000, v250
	global_load_dwordx4 v[200:203], v251, s[12:13]
	v_pk_add_f32 v[126:127], v[126:127], v[136:137]
	v_pk_add_f32 v[128:129], v[128:129], v[138:139]
	v_pk_mul_f32 v[138:139], v[94:95], v[126:127]
	global_store_dwordx4 v[142:143], v[126:129], off
	v_pk_mul_f32 v[136:137], v[96:97], v[128:129]
	v_cvt_pk_bf16_f32 v138, v138, v139
	s_nop 0
	v_cvt_pk_bf16_f32 v139, v136, v137
	global_store_dwordx2 v[140:141], v[138:139], off
	v_mul_f32_e32 v127, v127, v127
	v_mul_f32_e32 v129, v129, v129
	v_fmac_f32_e32 v127, v126, v126
	v_fmac_f32_e32 v129, v128, v128
	v_add_f32_e32 v126, v127, v129
	s_waitcnt vmcnt(15)
	s_nop 1
	v_mov_b64_e32 v[136:137], v[204:205]
	v_mov_b64_e32 v[138:139], v[206:207]
	v_add_u32_e32 v251, 0x120000, v250
	global_load_dwordx4 v[204:207], v251, s[12:13] offset:64
	v_pk_add_f32 v[122:123], v[122:123], v[136:137]
	v_pk_add_f32 v[124:125], v[124:125], v[138:139]
	v_pk_mul_f32 v[138:139], v[90:91], v[122:123]
	global_store_dwordx4 v[142:143], v[122:125], off offset:64
	v_pk_mul_f32 v[136:137], v[92:93], v[124:125]
	v_cvt_pk_bf16_f32 v138, v138, v139
	s_nop 0
	v_cvt_pk_bf16_f32 v139, v136, v137
	global_store_dwordx2 v[140:141], v[138:139], off offset:32
	v_mul_f32_e32 v123, v123, v123
	v_mul_f32_e32 v125, v125, v125
	v_fmac_f32_e32 v123, v122, v122
	v_fmac_f32_e32 v125, v124, v124
	v_add_f32_e32 v122, v123, v125
	v_add_f32_e32 v122, v126, v122
	s_waitcnt vmcnt(15)
	s_nop 1
	v_mov_b64_e32 v[136:137], v[208:209]
	v_mov_b64_e32 v[138:139], v[210:211]
	v_add_u32_e32 v251, 0x120000, v250
	global_load_dwordx4 v[208:211], v251, s[12:13] offset:512
	v_pk_add_f32 v[118:119], v[118:119], v[136:137]
	v_pk_add_f32 v[120:121], v[120:121], v[138:139]
	v_pk_mul_f32 v[138:139], v[82:83], v[118:119]
	global_store_dwordx4 v[142:143], v[118:121], off offset:512
	v_pk_mul_f32 v[136:137], v[84:85], v[120:121]
	v_cvt_pk_bf16_f32 v138, v138, v139
	s_nop 0
	v_cvt_pk_bf16_f32 v139, v136, v137
	global_store_dwordx2 v[140:141], v[138:139], off offset:256
	v_mul_f32_e32 v119, v119, v119
	v_mul_f32_e32 v121, v121, v121
	v_fmac_f32_e32 v119, v118, v118
	v_fmac_f32_e32 v121, v120, v120
	v_add_f32_e32 v118, v119, v121
	v_add_f32_e32 v120, v122, v118
	s_waitcnt vmcnt(15)
	s_nop 1
	v_mov_b64_e32 v[136:137], v[212:213]
	v_mov_b64_e32 v[138:139], v[214:215]
	v_add_u32_e32 v251, 0x120000, v250
	global_load_dwordx4 v[212:215], v251, s[12:13] offset:576
	v_pk_add_f32 v[118:119], v[116:117], v[138:139]
	v_pk_add_f32 v[116:117], v[114:115], v[136:137]
	v_mul_f32_e32 v115, v119, v119
	v_mul_f32_e32 v114, v117, v117
	v_fmac_f32_e32 v114, v116, v116
	v_fmac_f32_e32 v115, v118, v118
	v_add_f32_e32 v114, v114, v115
	v_add_f32_e32 v114, v120, v114
	ds_bpermute_b32 v115, v134, v114
	global_store_dwordx4 v[142:143], v[116:119], off offset:576
	s_waitcnt lgkmcnt(0)
	v_add_f32_e32 v114, v114, v115
	ds_bpermute_b32 v115, v132, v114
	v_pk_mul_f32 v[116:117], v[70:71], v[116:117]
	v_pk_mul_f32 v[118:119], v[72:73], v[118:119]
	v_cvt_pk_bf16_f32 v116, v116, v117
	s_nop 0
	v_cvt_pk_bf16_f32 v117, v118, v119
	global_store_dwordx2 v[140:141], v[116:117], off offset:288
	s_and_saveexec_b64 s[56:57], s[2:3]
	s_cbranch_execz .LBB0_927
	v_lshl_add_u64 v[116:117], v[130:131], 2, s[6:7]
	s_waitcnt lgkmcnt(0)
	v_add_f32_e32 v114, v114, v115
	global_atomic_add_f32 v[116:117], v114, off
.LBB0_927:
	s_or_b64 exec, exec, s[56:57]
	v_or_b32_e32 v114, 32, v160
	s_waitcnt lgkmcnt(0)
	v_ashrrev_i32_e32 v115, 31, v114
	v_lshlrev_b64 v[116:117], 11, v[114:115]
	v_lshl_add_u64 v[120:121], v[116:117], 0, v[158:159]
	v_lshl_add_u64 v[122:123], v[120:121], 2, s[12:13]
	v_lshl_add_u64 v[120:121], v[120:121], 1, s[30:31]
	s_waitcnt vmcnt(15)
	s_nop 1
	v_mov_b64_e32 v[116:117], v[216:217]
	v_mov_b64_e32 v[118:119], v[218:219]
	v_add_u32_e32 v251, 0x140000, v250
	global_load_dwordx4 v[216:219], v251, s[12:13]
	v_pk_add_f32 v[110:111], v[110:111], v[116:117]
	v_pk_add_f32 v[112:113], v[112:113], v[118:119]
	v_pk_mul_f32 v[118:119], v[94:95], v[110:111]
	global_store_dwordx4 v[122:123], v[110:113], off
	v_pk_mul_f32 v[116:117], v[96:97], v[112:113]
	v_cvt_pk_bf16_f32 v118, v118, v119
	s_nop 0
	v_cvt_pk_bf16_f32 v119, v116, v117
	global_store_dwordx2 v[120:121], v[118:119], off
	v_mul_f32_e32 v111, v111, v111
	v_mul_f32_e32 v113, v113, v113
	v_fmac_f32_e32 v111, v110, v110
	v_fmac_f32_e32 v113, v112, v112
	v_add_f32_e32 v110, v111, v113
	s_waitcnt vmcnt(15)
	s_nop 1
	v_mov_b64_e32 v[116:117], v[220:221]
	v_mov_b64_e32 v[118:119], v[222:223]
	v_add_u32_e32 v251, 0x140000, v250
	global_load_dwordx4 v[220:223], v251, s[12:13] offset:64
	v_pk_add_f32 v[106:107], v[106:107], v[116:117]
	v_pk_add_f32 v[108:109], v[108:109], v[118:119]
	v_pk_mul_f32 v[118:119], v[90:91], v[106:107]
	global_store_dwordx4 v[122:123], v[106:109], off offset:64
	v_pk_mul_f32 v[116:117], v[92:93], v[108:109]
	v_cvt_pk_bf16_f32 v118, v118, v119
	s_nop 0
	v_cvt_pk_bf16_f32 v119, v116, v117
	global_store_dwordx2 v[120:121], v[118:119], off offset:32
	v_mul_f32_e32 v107, v107, v107
	v_mul_f32_e32 v109, v109, v109
	v_fmac_f32_e32 v107, v106, v106
	v_fmac_f32_e32 v109, v108, v108
	v_add_f32_e32 v106, v107, v109
	v_add_f32_e32 v106, v110, v106
	s_waitcnt vmcnt(15)
; __device__ __forceinline__ unsigned pk2(float lo, float hi) { return cvt_pk_bf16(lo, hi); }
;     __device__ __forceinline__ void operator()(const f32x4 (&acc)[2][2][4][2], const Unit& u, int wr, int wc, int fr, int fq) const {
;     ...
;         for (int ai = 0; ai < 2; ++ai)
; #pragma unroll
;             for (int m = 0; m < 4; ++m) {
;                 const int row = row0 + ai * 128 + m * 16; const size_t off = (size_t)row * D + col0;
;                 float s = 0.f;
; #pragma unroll
;                 for (int bj = 0; bj < 2; ++bj)
; #pragma unroll
;                     for (int n = 0; n < 2; ++n) { const f32x4 b = *(const f32x4*)(base + off + bj * 128 + n * 16); const f32x4 o = b + acc[ai][bj][m][n];
;                         *(f32x4*)(out + off + bj * 128 + n * 16) = o; s += (o[0] * o[0] + o[1] * o[1]) + (o[2] * o[2] + o[3] * o[3]);
;                         const f32x4 y = o * gv[bj][n]; u32x2 w; w.x = pk2(y[0], y[1]); w.y = pk2(y[2], y[3]); *(u32x2*)(xg + off + bj * 128 + n * 16) = w; }
;                 s += __shfl_xor(s, 16); s += __shfl_xor(s, 32);
;                 if (fq == 0) atomicAdd(ssq + row, s);
;             }
	s_nop 1
	v_mov_b64_e32 v[116:117], v[224:225]
	v_mov_b64_e32 v[118:119], v[226:227]
	v_add_u32_e32 v251, 0x140000, v250
	global_load_dwordx4 v[224:227], v251, s[12:13] offset:512
	v_pk_add_f32 v[102:103], v[102:103], v[116:117]
	v_pk_add_f32 v[104:105], v[104:105], v[118:119]
	v_pk_mul_f32 v[118:119], v[82:83], v[102:103]
	global_store_dwordx4 v[122:123], v[102:105], off offset:512
	v_pk_mul_f32 v[116:117], v[84:85], v[104:105]
	v_cvt_pk_bf16_f32 v118, v118, v119
	s_nop 0
	v_cvt_pk_bf16_f32 v119, v116, v117
	global_store_dwordx2 v[120:121], v[118:119], off offset:256
	v_mul_f32_e32 v103, v103, v103
	v_mul_f32_e32 v105, v105, v105
	v_fmac_f32_e32 v103, v102, v102
	v_fmac_f32_e32 v105, v104, v104
	v_add_f32_e32 v102, v103, v105
	v_add_f32_e32 v104, v106, v102
	s_waitcnt vmcnt(15)
	s_nop 1
	v_mov_b64_e32 v[116:117], v[228:229]
	v_mov_b64_e32 v[118:119], v[230:231]
	v_add_u32_e32 v251, 0x140000, v250
	global_load_dwordx4 v[228:231], v251, s[12:13] offset:576
	v_pk_add_f32 v[102:103], v[100:101], v[118:119]
	v_pk_add_f32 v[100:101], v[98:99], v[116:117]
	v_mul_f32_e32 v99, v103, v103
	v_mul_f32_e32 v98, v101, v101
	v_fmac_f32_e32 v98, v100, v100
	v_fmac_f32_e32 v99, v102, v102
	v_add_f32_e32 v98, v98, v99
	v_add_f32_e32 v98, v104, v98
	ds_bpermute_b32 v99, v134, v98
	global_store_dwordx4 v[122:123], v[100:103], off offset:576
	s_waitcnt lgkmcnt(0)
	v_add_f32_e32 v98, v98, v99
	ds_bpermute_b32 v99, v132, v98
	v_pk_mul_f32 v[100:101], v[70:71], v[100:101]
	v_pk_mul_f32 v[102:103], v[72:73], v[102:103]
	v_cvt_pk_bf16_f32 v100, v100, v101
	s_nop 0
	v_cvt_pk_bf16_f32 v101, v102, v103
	global_store_dwordx2 v[120:121], v[100:101], off offset:288
	s_and_saveexec_b64 s[56:57], s[2:3]
	s_cbranch_execz .LBB0_929
	v_lshl_add_u64 v[100:101], v[114:115], 2, s[6:7]
	s_waitcnt lgkmcnt(0)
	v_add_f32_e32 v98, v98, v99
	global_atomic_add_f32 v[100:101], v98, off
.LBB0_929:
	s_or_b64 exec, exec, s[56:57]
	v_or_b32_e32 v98, 48, v160
	s_waitcnt lgkmcnt(0)
	v_ashrrev_i32_e32 v99, 31, v98
	v_lshlrev_b64 v[100:101], 11, v[98:99]
	v_lshl_add_u64 v[104:105], v[100:101], 0, v[158:159]
	v_lshl_add_u64 v[106:107], v[104:105], 2, s[12:13]
	v_lshl_add_u64 v[104:105], v[104:105], 1, s[30:31]
	s_waitcnt vmcnt(15)
	s_nop 1
	v_mov_b64_e32 v[100:101], v[232:233]
	v_mov_b64_e32 v[102:103], v[234:235]
	v_add_u32_e32 v251, 0x160000, v250
	global_load_dwordx4 v[232:235], v251, s[12:13]
	v_pk_add_f32 v[86:87], v[86:87], v[100:101]
	v_pk_add_f32 v[88:89], v[88:89], v[102:103]
	v_pk_mul_f32 v[102:103], v[94:95], v[86:87]
	global_store_dwordx4 v[106:107], v[86:89], off
	v_pk_mul_f32 v[100:101], v[96:97], v[88:89]
	v_cvt_pk_bf16_f32 v102, v102, v103
	s_nop 0
	v_cvt_pk_bf16_f32 v103, v100, v101
	global_store_dwordx2 v[104:105], v[102:103], off
	v_mul_f32_e32 v87, v87, v87
	v_mul_f32_e32 v89, v89, v89
	v_fmac_f32_e32 v87, v86, v86
	v_fmac_f32_e32 v89, v88, v88
	v_add_f32_e32 v86, v87, v89
	s_waitcnt vmcnt(15)
	s_nop 1
	v_mov_b64_e32 v[100:101], v[236:237]
	v_mov_b64_e32 v[102:103], v[238:239]
	v_add_u32_e32 v251, 0x160000, v250
	global_load_dwordx4 v[236:239], v251, s[12:13] offset:64
	v_pk_add_f32 v[78:79], v[78:79], v[100:101]
	v_pk_add_f32 v[80:81], v[80:81], v[102:103]
	v_pk_mul_f32 v[102:103], v[90:91], v[78:79]
	global_store_dwordx4 v[106:107], v[78:81], off offset:64
	v_pk_mul_f32 v[100:101], v[92:93], v[80:81]
	v_cvt_pk_bf16_f32 v102, v102, v103
	s_nop 0
	v_cvt_pk_bf16_f32 v103, v100, v101
	global_store_dwordx2 v[104:105], v[102:103], off offset:32
	v_mul_f32_e32 v79, v79, v79
	v_mul_f32_e32 v81, v81, v81
	v_fmac_f32_e32 v79, v78, v78
	v_fmac_f32_e32 v81, v80, v80
	v_add_f32_e32 v78, v79, v81
	v_add_f32_e32 v78, v86, v78
	s_waitcnt vmcnt(15)
	s_nop 1
	v_mov_b64_e32 v[100:101], v[240:241]
	v_mov_b64_e32 v[102:103], v[242:243]
	v_add_u32_e32 v251, 0x160000, v250
	global_load_dwordx4 v[240:243], v251, s[12:13] offset:512
	v_pk_add_f32 v[74:75], v[74:75], v[100:101]
	v_pk_add_f32 v[76:77], v[76:77], v[102:103]
	v_pk_mul_f32 v[102:103], v[82:83], v[74:75]
	global_store_dwordx4 v[106:107], v[74:77], off offset:512
	v_pk_mul_f32 v[100:101], v[84:85], v[76:77]
	v_cvt_pk_bf16_f32 v102, v102, v103
	s_nop 0
	v_cvt_pk_bf16_f32 v103, v100, v101
	global_store_dwordx2 v[104:105], v[102:103], off offset:256
	v_mul_f32_e32 v75, v75, v75
	v_mul_f32_e32 v77, v77, v77
	v_fmac_f32_e32 v75, v74, v74
	v_fmac_f32_e32 v77, v76, v76
	v_add_f32_e32 v74, v75, v77
	v_add_f32_e32 v78, v78, v74
	s_waitcnt vmcnt(15)
	s_nop 1
	v_mov_b64_e32 v[100:101], v[244:245]
	v_mov_b64_e32 v[102:103], v[246:247]
	v_add_u32_e32 v251, 0x160000, v250
	global_load_dwordx4 v[244:247], v251, s[12:13] offset:576
	v_pk_add_f32 v[76:77], v[68:69], v[102:103]
	v_pk_add_f32 v[74:75], v[66:67], v[100:101]
	v_mul_f32_e32 v67, v77, v77
	v_mul_f32_e32 v66, v75, v75
	v_fmac_f32_e32 v66, v74, v74
	v_fmac_f32_e32 v67, v76, v76
	v_add_f32_e32 v66, v66, v67
	v_add_f32_e32 v66, v78, v66
	ds_bpermute_b32 v67, v134, v66
	global_store_dwordx4 v[106:107], v[74:77], off offset:576
	v_pk_mul_f32 v[68:69], v[72:73], v[76:77]
	s_waitcnt lgkmcnt(0)
	v_add_f32_e32 v66, v66, v67
	ds_bpermute_b32 v67, v132, v66
	v_pk_mul_f32 v[74:75], v[70:71], v[74:75]
	s_nop 0
	v_cvt_pk_bf16_f32 v74, v74, v75
	v_cvt_pk_bf16_f32 v75, v68, v69
	global_store_dwordx2 v[104:105], v[74:75], off offset:288
	s_and_saveexec_b64 s[56:57], s[2:3]
	s_cbranch_execz .LBB0_931
	v_lshl_add_u64 v[68:69], v[98:99], 2, s[6:7]
	s_waitcnt lgkmcnt(0)
	v_add_f32_e32 v66, v66, v67
	global_atomic_add_f32 v[68:69], v66, off
; __device__ __forceinline__ unsigned pk2(float lo, float hi) { return cvt_pk_bf16(lo, hi); }
;     __device__ __forceinline__ void operator()(const f32x4 (&acc)[2][2][4][2], const Unit& u, int wr, int wc, int fr, int fq) const {
;     ...
;         for (int ai = 0; ai < 2; ++ai)
; #pragma unroll
;             for (int m = 0; m < 4; ++m) {
;                 const int row = row0 + ai * 128 + m * 16; const size_t off = (size_t)row * D + col0;
;                 float s = 0.f;
; #pragma unroll
;                 for (int bj = 0; bj < 2; ++bj)
; #pragma unroll
;                     for (int n = 0; n < 2; ++n) { const f32x4 b = *(const f32x4*)(base + off + bj * 128 + n * 16); const f32x4 o = b + acc[ai][bj][m][n];
;                         *(f32x4*)(out + off + bj * 128 + n * 16) = o; s += (o[0] * o[0] + o[1] * o[1]) + (o[2] * o[2] + o[3] * o[3]);
;                         const f32x4 y = o * gv[bj][n]; u32x2 w; w.x = pk2(y[0], y[1]); w.y = pk2(y[2], y[3]); *(u32x2*)(xg + off + bj * 128 + n * 16) = w; }
;                 s += __shfl_xor(s, 16); s += __shfl_xor(s, 32);
;                 if (fq == 0) atomicAdd(ssq + row, s);
;             }
.LBB0_931:
	s_or_b64 exec, exec, s[56:57]
	v_add_u32_e32 v66, 0x80, v160
	s_waitcnt lgkmcnt(0)
	v_ashrrev_i32_e32 v67, 31, v66
	v_lshlrev_b64 v[68:69], 11, v[66:67]
	v_lshl_add_u64 v[68:69], v[68:69], 0, v[158:159]
	v_lshl_add_u64 v[78:79], v[68:69], 2, s[12:13]
	v_lshl_add_u64 v[68:69], v[68:69], 1, s[30:31]
	s_waitcnt vmcnt(15)
	s_nop 1
	v_mov_b64_e32 v[74:75], v[184:185]
	v_mov_b64_e32 v[76:77], v[186:187]
	v_pk_add_f32 v[62:63], v[62:63], v[74:75]
	v_pk_add_f32 v[64:65], v[64:65], v[76:77]
	v_pk_mul_f32 v[76:77], v[94:95], v[62:63]
	global_store_dwordx4 v[78:79], v[62:65], off
	v_pk_mul_f32 v[74:75], v[96:97], v[64:65]
	v_cvt_pk_bf16_f32 v76, v76, v77
	s_nop 0
	v_cvt_pk_bf16_f32 v77, v74, v75
	global_store_dwordx2 v[68:69], v[76:77], off
	v_mul_f32_e32 v63, v63, v63
	v_mul_f32_e32 v65, v65, v65
	v_fmac_f32_e32 v63, v62, v62
	v_fmac_f32_e32 v65, v64, v64
	v_add_f32_e32 v62, v63, v65
	s_waitcnt vmcnt(14)
	s_nop 1
	v_mov_b64_e32 v[74:75], v[188:189]
	v_mov_b64_e32 v[76:77], v[190:191]
	v_pk_add_f32 v[58:59], v[58:59], v[74:75]
	v_pk_add_f32 v[60:61], v[60:61], v[76:77]
	v_pk_mul_f32 v[76:77], v[90:91], v[58:59]
	global_store_dwordx4 v[78:79], v[58:61], off offset:64
	v_pk_mul_f32 v[74:75], v[92:93], v[60:61]
	v_cvt_pk_bf16_f32 v76, v76, v77
	s_nop 0
	v_cvt_pk_bf16_f32 v77, v74, v75
	global_store_dwordx2 v[68:69], v[76:77], off offset:32
	v_mul_f32_e32 v59, v59, v59
	v_mul_f32_e32 v61, v61, v61
	v_fmac_f32_e32 v59, v58, v58
	v_fmac_f32_e32 v61, v60, v60
	v_add_f32_e32 v58, v59, v61
	v_add_f32_e32 v58, v62, v58
	s_waitcnt vmcnt(13)
	s_nop 1
	v_mov_b64_e32 v[74:75], v[192:193]
	v_mov_b64_e32 v[76:77], v[194:195]
	v_pk_add_f32 v[54:55], v[54:55], v[74:75]
	v_pk_add_f32 v[56:57], v[56:57], v[76:77]
	v_pk_mul_f32 v[76:77], v[82:83], v[54:55]
	global_store_dwordx4 v[78:79], v[54:57], off offset:512
	v_pk_mul_f32 v[74:75], v[84:85], v[56:57]
	v_cvt_pk_bf16_f32 v76, v76, v77
	s_nop 0
	v_cvt_pk_bf16_f32 v77, v74, v75
	global_store_dwordx2 v[68:69], v[76:77], off offset:256
	v_mul_f32_e32 v55, v55, v55
	v_mul_f32_e32 v57, v57, v57
	v_fmac_f32_e32 v55, v54, v54
	v_fmac_f32_e32 v57, v56, v56
	v_add_f32_e32 v54, v55, v57
	v_add_f32_e32 v56, v58, v54
	s_waitcnt vmcnt(12)
	s_nop 1
	v_mov_b64_e32 v[74:75], v[196:197]
	v_mov_b64_e32 v[76:77], v[198:199]
	v_pk_add_f32 v[54:55], v[52:53], v[76:77]
	v_pk_add_f32 v[52:53], v[50:51], v[74:75]
	v_mul_f32_e32 v51, v55, v55
	v_mul_f32_e32 v50, v53, v53
	v_fmac_f32_e32 v50, v52, v52
	v_fmac_f32_e32 v51, v54, v54
	v_add_f32_e32 v50, v50, v51
	v_add_f32_e32 v50, v56, v50
	ds_bpermute_b32 v51, v134, v50
	global_store_dwordx4 v[78:79], v[52:55], off offset:576
	s_waitcnt lgkmcnt(0)
	v_add_f32_e32 v50, v50, v51
	ds_bpermute_b32 v51, v132, v50
	v_pk_mul_f32 v[52:53], v[70:71], v[52:53]
	v_pk_mul_f32 v[54:55], v[72:73], v[54:55]
	v_cvt_pk_bf16_f32 v52, v52, v53
	s_nop 0
	v_cvt_pk_bf16_f32 v53, v54, v55
	global_store_dwordx2 v[68:69], v[52:53], off offset:288
	s_and_saveexec_b64 s[56:57], s[2:3]
	s_cbranch_execz .LBB0_933
	v_lshl_add_u64 v[52:53], v[66:67], 2, s[6:7]
	s_waitcnt lgkmcnt(0)
	v_add_f32_e32 v50, v50, v51
	global_atomic_add_f32 v[52:53], v50, off
.LBB0_933:
	s_or_b64 exec, exec, s[56:57]
	v_add_u32_e32 v50, 0x90, v160
	s_waitcnt lgkmcnt(0)
	v_ashrrev_i32_e32 v51, 31, v50
	v_lshlrev_b64 v[52:53], 11, v[50:51]
	v_lshl_add_u64 v[56:57], v[52:53], 0, v[158:159]
	v_lshl_add_u64 v[58:59], v[56:57], 2, s[12:13]
	v_lshl_add_u64 v[56:57], v[56:57], 1, s[30:31]
	s_waitcnt vmcnt(11)
	s_nop 1
	v_mov_b64_e32 v[52:53], v[200:201]
	v_mov_b64_e32 v[54:55], v[202:203]
	v_pk_add_f32 v[46:47], v[46:47], v[52:53]
	v_pk_add_f32 v[48:49], v[48:49], v[54:55]
	v_pk_mul_f32 v[54:55], v[94:95], v[46:47]
	global_store_dwordx4 v[58:59], v[46:49], off
	v_pk_mul_f32 v[52:53], v[96:97], v[48:49]
	v_cvt_pk_bf16_f32 v54, v54, v55
	s_nop 0
	v_cvt_pk_bf16_f32 v55, v52, v53
	global_store_dwordx2 v[56:57], v[54:55], off
	v_mul_f32_e32 v47, v47, v47
	v_mul_f32_e32 v49, v49, v49
	v_fmac_f32_e32 v47, v46, v46
	v_fmac_f32_e32 v49, v48, v48
	v_add_f32_e32 v46, v47, v49
	s_waitcnt vmcnt(10)
	s_nop 1
	v_mov_b64_e32 v[52:53], v[204:205]
	v_mov_b64_e32 v[54:55], v[206:207]
	v_pk_add_f32 v[42:43], v[42:43], v[52:53]
	v_pk_add_f32 v[44:45], v[44:45], v[54:55]
	v_pk_mul_f32 v[54:55], v[90:91], v[42:43]
	global_store_dwordx4 v[58:59], v[42:45], off offset:64
	v_pk_mul_f32 v[52:53], v[92:93], v[44:45]
	v_cvt_pk_bf16_f32 v54, v54, v55
	s_nop 0
	v_cvt_pk_bf16_f32 v55, v52, v53
	global_store_dwordx2 v[56:57], v[54:55], off offset:32
	v_mul_f32_e32 v43, v43, v43
	v_mul_f32_e32 v45, v45, v45
	v_fmac_f32_e32 v43, v42, v42
	v_fmac_f32_e32 v45, v44, v44
	v_add_f32_e32 v42, v43, v45
	v_add_f32_e32 v42, v46, v42
	s_waitcnt vmcnt(9)
	s_nop 1
	v_mov_b64_e32 v[52:53], v[208:209]
	v_mov_b64_e32 v[54:55], v[210:211]
	v_pk_add_f32 v[38:39], v[38:39], v[52:53]
	v_pk_add_f32 v[40:41], v[40:41], v[54:55]
	v_pk_mul_f32 v[54:55], v[82:83], v[38:39]
	global_store_dwordx4 v[58:59], v[38:41], off offset:512
	v_pk_mul_f32 v[52:53], v[84:85], v[40:41]
	v_cvt_pk_bf16_f32 v54, v54, v55
	s_nop 0
	v_cvt_pk_bf16_f32 v55, v52, v53
	global_store_dwordx2 v[56:57], v[54:55], off offset:256
	v_mul_f32_e32 v39, v39, v39
	v_mul_f32_e32 v41, v41, v41
	v_fmac_f32_e32 v39, v38, v38
	v_fmac_f32_e32 v41, v40, v40
	v_add_f32_e32 v38, v39, v41
	v_add_f32_e32 v40, v42, v38
	s_waitcnt vmcnt(8)
	s_nop 1
	v_mov_b64_e32 v[52:53], v[212:213]
	v_mov_b64_e32 v[54:55], v[214:215]
	v_pk_add_f32 v[38:39], v[36:37], v[54:55]
	v_pk_add_f32 v[36:37], v[34:35], v[52:53]
	v_mul_f32_e32 v35, v39, v39
	v_mul_f32_e32 v34, v37, v37
	v_fmac_f32_e32 v34, v36, v36
	v_fmac_f32_e32 v35, v38, v38
	v_add_f32_e32 v34, v34, v35
	v_add_f32_e32 v34, v40, v34
	ds_bpermute_b32 v35, v134, v34
	global_store_dwordx4 v[58:59], v[36:39], off offset:576
	s_waitcnt lgkmcnt(0)
	v_add_f32_e32 v34, v34, v35
	ds_bpermute_b32 v35, v132, v34
	v_pk_mul_f32 v[36:37], v[70:71], v[36:37]
	v_pk_mul_f32 v[38:39], v[72:73], v[38:39]
	v_cvt_pk_bf16_f32 v36, v36, v37
	s_nop 0
	v_cvt_pk_bf16_f32 v37, v38, v39
	global_store_dwordx2 v[56:57], v[36:37], off offset:288
	s_and_saveexec_b64 s[56:57], s[2:3]
	s_cbranch_execz .LBB0_935
	v_lshl_add_u64 v[36:37], v[50:51], 2, s[6:7]
	s_waitcnt lgkmcnt(0)
	v_add_f32_e32 v34, v34, v35
	global_atomic_add_f32 v[36:37], v34, off
; __device__ __forceinline__ unsigned pk2(float lo, float hi) { return cvt_pk_bf16(lo, hi); }
;     __device__ __forceinline__ void operator()(const f32x4 (&acc)[2][2][4][2], const Unit& u, int wr, int wc, int fr, int fq) const {
;     ...
;         for (int ai = 0; ai < 2; ++ai)
; #pragma unroll
;             for (int m = 0; m < 4; ++m) {
;                 const int row = row0 + ai * 128 + m * 16; const size_t off = (size_t)row * D + col0;
;                 float s = 0.f;
; #pragma unroll
;                 for (int bj = 0; bj < 2; ++bj)
; #pragma unroll
;                     for (int n = 0; n < 2; ++n) { const f32x4 b = *(const f32x4*)(base + off + bj * 128 + n * 16); const f32x4 o = b + acc[ai][bj][m][n];
;                         *(f32x4*)(out + off + bj * 128 + n * 16) = o; s += (o[0] * o[0] + o[1] * o[1]) + (o[2] * o[2] + o[3] * o[3]);
;                         const f32x4 y = o * gv[bj][n]; u32x2 w; w.x = pk2(y[0], y[1]); w.y = pk2(y[2], y[3]); *(u32x2*)(xg + off + bj * 128 + n * 16) = w; }
;                 s += __shfl_xor(s, 16); s += __shfl_xor(s, 32);
;                 if (fq == 0) atomicAdd(ssq + row, s);
;             }
.LBB0_935:
	s_or_b64 exec, exec, s[56:57]
	v_add_u32_e32 v34, 0xa0, v160
	s_waitcnt lgkmcnt(0)
	v_ashrrev_i32_e32 v35, 31, v34
	v_lshlrev_b64 v[36:37], 11, v[34:35]
	v_lshl_add_u64 v[40:41], v[36:37], 0, v[158:159]
	v_lshl_add_u64 v[42:43], v[40:41], 2, s[12:13]
	v_lshl_add_u64 v[40:41], v[40:41], 1, s[30:31]
	s_waitcnt vmcnt(7)
	s_nop 1
	v_mov_b64_e32 v[36:37], v[216:217]
	v_mov_b64_e32 v[38:39], v[218:219]
	v_pk_add_f32 v[30:31], v[30:31], v[36:37]
	v_pk_add_f32 v[32:33], v[32:33], v[38:39]
	v_pk_mul_f32 v[38:39], v[94:95], v[30:31]
	global_store_dwordx4 v[42:43], v[30:33], off
	v_pk_mul_f32 v[36:37], v[96:97], v[32:33]
	v_cvt_pk_bf16_f32 v38, v38, v39
	s_nop 0
	v_cvt_pk_bf16_f32 v39, v36, v37
	global_store_dwordx2 v[40:41], v[38:39], off
	v_mul_f32_e32 v31, v31, v31
	v_mul_f32_e32 v33, v33, v33
	v_fmac_f32_e32 v31, v30, v30
	v_fmac_f32_e32 v33, v32, v32
	v_add_f32_e32 v30, v31, v33
	s_waitcnt vmcnt(6)
	s_nop 1
	v_mov_b64_e32 v[36:37], v[220:221]
	v_mov_b64_e32 v[38:39], v[222:223]
	v_pk_add_f32 v[26:27], v[26:27], v[36:37]
	v_pk_add_f32 v[28:29], v[28:29], v[38:39]
	v_pk_mul_f32 v[38:39], v[90:91], v[26:27]
	global_store_dwordx4 v[42:43], v[26:29], off offset:64
	v_pk_mul_f32 v[36:37], v[92:93], v[28:29]
	v_cvt_pk_bf16_f32 v38, v38, v39
	s_nop 0
	v_cvt_pk_bf16_f32 v39, v36, v37
	global_store_dwordx2 v[40:41], v[38:39], off offset:32
	v_mul_f32_e32 v27, v27, v27
	v_mul_f32_e32 v29, v29, v29
	v_fmac_f32_e32 v27, v26, v26
	v_fmac_f32_e32 v29, v28, v28
	v_add_f32_e32 v26, v27, v29
	v_add_f32_e32 v26, v30, v26
	s_waitcnt vmcnt(5)
	s_nop 1
	v_mov_b64_e32 v[36:37], v[224:225]
	v_mov_b64_e32 v[38:39], v[226:227]
	v_pk_add_f32 v[22:23], v[22:23], v[36:37]
	v_pk_add_f32 v[24:25], v[24:25], v[38:39]
	v_pk_mul_f32 v[38:39], v[82:83], v[22:23]
	global_store_dwordx4 v[42:43], v[22:25], off offset:512
	v_pk_mul_f32 v[36:37], v[84:85], v[24:25]
	v_cvt_pk_bf16_f32 v38, v38, v39
	s_nop 0
	v_cvt_pk_bf16_f32 v39, v36, v37
	global_store_dwordx2 v[40:41], v[38:39], off offset:256
	v_mul_f32_e32 v23, v23, v23
	v_mul_f32_e32 v25, v25, v25
	v_fmac_f32_e32 v23, v22, v22
	v_fmac_f32_e32 v25, v24, v24
	v_add_f32_e32 v22, v23, v25
	v_add_f32_e32 v24, v26, v22
	s_waitcnt vmcnt(4)
	s_nop 1
	v_mov_b64_e32 v[36:37], v[228:229]
	v_mov_b64_e32 v[38:39], v[230:231]
	v_pk_add_f32 v[22:23], v[20:21], v[38:39]
	v_pk_add_f32 v[20:21], v[18:19], v[36:37]
	v_mul_f32_e32 v19, v23, v23
	v_mul_f32_e32 v18, v21, v21
	v_fmac_f32_e32 v18, v20, v20
	v_fmac_f32_e32 v19, v22, v22
	v_add_f32_e32 v18, v18, v19
	v_add_f32_e32 v18, v24, v18
	ds_bpermute_b32 v19, v134, v18
	global_store_dwordx4 v[42:43], v[20:23], off offset:576
	s_waitcnt lgkmcnt(0)
	v_add_f32_e32 v18, v18, v19
	ds_bpermute_b32 v19, v132, v18
	v_pk_mul_f32 v[20:21], v[70:71], v[20:21]
	v_pk_mul_f32 v[22:23], v[72:73], v[22:23]
	v_cvt_pk_bf16_f32 v20, v20, v21
	s_nop 0
	v_cvt_pk_bf16_f32 v21, v22, v23
	global_store_dwordx2 v[40:41], v[20:21], off offset:288
	s_and_saveexec_b64 s[56:57], s[2:3]
	s_cbranch_execz .LBB0_937
	v_lshl_add_u64 v[20:21], v[34:35], 2, s[6:7]
	s_waitcnt lgkmcnt(0)
	v_add_f32_e32 v18, v18, v19
	global_atomic_add_f32 v[20:21], v18, off
.LBB0_937:
	s_or_b64 exec, exec, s[56:57]
	v_add_u32_e32 v18, 0xb0, v160
	s_waitcnt lgkmcnt(0)
	v_ashrrev_i32_e32 v19, 31, v18
	v_lshlrev_b64 v[20:21], 11, v[18:19]
	v_lshl_add_u64 v[24:25], v[20:21], 0, v[158:159]
	v_lshl_add_u64 v[26:27], v[24:25], 2, s[12:13]
	v_lshl_add_u64 v[24:25], v[24:25], 1, s[30:31]
	s_waitcnt vmcnt(3)
	s_nop 1
	v_mov_b64_e32 v[20:21], v[232:233]
	v_mov_b64_e32 v[22:23], v[234:235]
	v_pk_add_f32 v[14:15], v[14:15], v[20:21]
	v_pk_add_f32 v[16:17], v[16:17], v[22:23]
	v_pk_mul_f32 v[22:23], v[94:95], v[14:15]
	global_store_dwordx4 v[26:27], v[14:17], off
	v_pk_mul_f32 v[20:21], v[96:97], v[16:17]
	v_cvt_pk_bf16_f32 v22, v22, v23
	s_nop 0
	v_cvt_pk_bf16_f32 v23, v20, v21
	global_store_dwordx2 v[24:25], v[22:23], off
	v_mul_f32_e32 v15, v15, v15
	v_mul_f32_e32 v17, v17, v17
	v_fmac_f32_e32 v15, v14, v14
	v_fmac_f32_e32 v17, v16, v16
	v_add_f32_e32 v14, v15, v17
	s_waitcnt vmcnt(2)
	s_nop 1
	v_mov_b64_e32 v[20:21], v[236:237]
	v_mov_b64_e32 v[22:23], v[238:239]
	v_pk_add_f32 v[10:11], v[10:11], v[20:21]
	v_pk_add_f32 v[12:13], v[12:13], v[22:23]
	v_pk_mul_f32 v[22:23], v[90:91], v[10:11]
	global_store_dwordx4 v[26:27], v[10:13], off offset:64
	v_pk_mul_f32 v[20:21], v[92:93], v[12:13]
	v_cvt_pk_bf16_f32 v22, v22, v23
	s_nop 0
	v_cvt_pk_bf16_f32 v23, v20, v21
	global_store_dwordx2 v[24:25], v[22:23], off offset:32
	v_mul_f32_e32 v11, v11, v11
	v_mul_f32_e32 v13, v13, v13
	v_fmac_f32_e32 v11, v10, v10
	v_fmac_f32_e32 v13, v12, v12
	v_add_f32_e32 v10, v11, v13
	v_add_f32_e32 v10, v14, v10
	s_waitcnt vmcnt(1)
	s_nop 1
	v_mov_b64_e32 v[20:21], v[240:241]
	v_mov_b64_e32 v[22:23], v[242:243]
	v_pk_add_f32 v[6:7], v[6:7], v[20:21]
	v_pk_add_f32 v[8:9], v[8:9], v[22:23]
	v_pk_mul_f32 v[22:23], v[82:83], v[6:7]
	global_store_dwordx4 v[26:27], v[6:9], off offset:512
	v_pk_mul_f32 v[20:21], v[84:85], v[8:9]
	v_cvt_pk_bf16_f32 v22, v22, v23
	s_nop 0
	v_cvt_pk_bf16_f32 v23, v20, v21
	global_store_dwordx2 v[24:25], v[22:23], off offset:256
	v_mul_f32_e32 v7, v7, v7
	v_mul_f32_e32 v9, v9, v9
	v_fmac_f32_e32 v7, v6, v6
	v_fmac_f32_e32 v9, v8, v8
	v_add_f32_e32 v6, v7, v9
	v_add_f32_e32 v8, v10, v6
	s_waitcnt vmcnt(0)
	s_nop 1
	v_mov_b64_e32 v[20:21], v[244:245]
	v_mov_b64_e32 v[22:23], v[246:247]
	v_pk_add_f32 v[6:7], v[4:5], v[22:23]
	v_pk_add_f32 v[4:5], v[2:3], v[20:21]
	v_mul_f32_e32 v3, v7, v7
	v_mul_f32_e32 v2, v5, v5
	v_fmac_f32_e32 v2, v4, v4
	v_fmac_f32_e32 v3, v6, v6
	v_add_f32_e32 v2, v2, v3
	v_add_f32_e32 v2, v8, v2
	ds_bpermute_b32 v3, v134, v2
	global_store_dwordx4 v[26:27], v[4:7], off offset:576
	s_waitcnt lgkmcnt(0)
	v_add_f32_e32 v2, v2, v3
	ds_bpermute_b32 v3, v132, v2
	v_pk_mul_f32 v[4:5], v[70:71], v[4:5]
	v_pk_mul_f32 v[6:7], v[72:73], v[6:7]
	v_cvt_pk_bf16_f32 v4, v4, v5
	s_nop 0
	v_cvt_pk_bf16_f32 v5, v6, v7
	global_store_dwordx2 v[24:25], v[4:5], off offset:288
	s_and_saveexec_b64 s[56:57], s[2:3]
	s_cbranch_execz .LBB0_939
	v_lshl_add_u64 v[4:5], v[18:19], 2, s[6:7]
	s_waitcnt lgkmcnt(0)
	v_add_f32_e32 v2, v2, v3
	global_atomic_add_f32 v[4:5], v2, off
